# GEMM loops: the two MFMAs of one accumulator (k=0,1 of the K-step) issued back to back instead of 8 apart
# speedup vs baseline: 1.0109x; 1.0109x over previous
.LBB0_200:
	ds_read_b128 v[148:151], v169
	ds_read_b128 v[152:155], v169 offset:1024
	ds_read_b128 v[156:159], v169 offset:2048
	ds_read_b128 v[160:163], v169 offset:3072
	ds_read_b128 v[174:177], v170
	ds_read_b128 v[178:181], v170 offset:1024
	ds_read_b128 v[182:185], v170 offset:2048
	ds_read_b128 v[186:189], v170 offset:3072
	s_add_u32 s26, s6, 0xfff00800
	s_addc_u32 s27, s7, -1
	s_cmp_eq_u32 s34, 60
	s_cselect_b32 s29, s17, s27
	s_cselect_b32 s28, s23, s26
	s_cselect_b32 s27, s15, s31
	s_cselect_b32 s26, s25, s30
	v_lshl_add_u64 v[190:191], s[6:7], 0, v[138:139]
	s_add_i32 m0, s41, 0xc000
	s_nop 0
	global_load_lds_dwordx4 v[190:191], off
	v_lshl_add_u64 v[190:191], s[6:7], 0, v[140:141]
	s_add_i32 m0, s41, 0xe000
	s_nop 0
	global_load_lds_dwordx4 v[190:191], off
	ds_read_b128 v[190:193], v171
	ds_read_b128 v[194:197], v171 offset:1024
	ds_read_b128 v[198:201], v171 offset:2048
	ds_read_b128 v[202:205], v171 offset:3072
	ds_read_b128 v[206:209], v171 offset:4096
	ds_read_b128 v[210:213], v171 offset:5120
	ds_read_b128 v[214:217], v171 offset:6144
	ds_read_b128 v[218:221], v171 offset:7168
	s_waitcnt vmcnt(8)
	s_waitcnt lgkmcnt(0)
	s_barrier
	s_setprio 1
	s_waitcnt lgkmcnt(0)
	v_mfma_f32_16x16x32_bf16 v[124:127], v[148:151], v[190:193], v[124:127]
	v_mfma_f32_16x16x32_bf16 v[124:127], v[152:155], v[194:197], v[124:127]
	v_mfma_f32_16x16x32_bf16 v[120:123], v[156:159], v[190:193], v[120:123]
	v_mfma_f32_16x16x32_bf16 v[120:123], v[160:163], v[194:197], v[120:123]
	v_mfma_f32_16x16x32_bf16 v[116:119], v[148:151], v[198:201], v[116:119]
	v_mfma_f32_16x16x32_bf16 v[116:119], v[152:155], v[202:205], v[116:119]
	v_mfma_f32_16x16x32_bf16 v[112:115], v[156:159], v[198:201], v[112:115]
	v_mfma_f32_16x16x32_bf16 v[112:115], v[160:163], v[202:205], v[112:115]
	v_mfma_f32_16x16x32_bf16 v[108:111], v[148:151], v[206:209], v[108:111]
	v_mfma_f32_16x16x32_bf16 v[108:111], v[152:155], v[210:213], v[108:111]
	v_mfma_f32_16x16x32_bf16 v[104:107], v[156:159], v[206:209], v[104:107]
	v_mfma_f32_16x16x32_bf16 v[104:107], v[160:163], v[210:213], v[104:107]
	v_mfma_f32_16x16x32_bf16 v[100:103], v[148:151], v[214:217], v[100:103]
	v_mfma_f32_16x16x32_bf16 v[100:103], v[152:155], v[218:221], v[100:103]
	v_mfma_f32_16x16x32_bf16 v[96:99], v[156:159], v[214:217], v[96:99]
	v_mfma_f32_16x16x32_bf16 v[96:99], v[160:163], v[218:221], v[96:99]
	s_setprio 0
	s_setprio 1
	v_mfma_f32_16x16x32_bf16 v[60:63], v[174:177], v[190:193], v[60:63]
	v_mfma_f32_16x16x32_bf16 v[60:63], v[178:181], v[194:197], v[60:63]
	v_mfma_f32_16x16x32_bf16 v[56:59], v[182:185], v[190:193], v[56:59]
	v_mfma_f32_16x16x32_bf16 v[56:59], v[186:189], v[194:197], v[56:59]
	v_mfma_f32_16x16x32_bf16 v[52:55], v[174:177], v[198:201], v[52:55]
	v_mfma_f32_16x16x32_bf16 v[52:55], v[178:181], v[202:205], v[52:55]
	v_mfma_f32_16x16x32_bf16 v[48:51], v[182:185], v[198:201], v[48:51]
	v_mfma_f32_16x16x32_bf16 v[48:51], v[186:189], v[202:205], v[48:51]
	v_mfma_f32_16x16x32_bf16 v[44:47], v[174:177], v[206:209], v[44:47]
	v_mfma_f32_16x16x32_bf16 v[44:47], v[178:181], v[210:213], v[44:47]
	v_mfma_f32_16x16x32_bf16 v[40:43], v[182:185], v[206:209], v[40:43]
	v_mfma_f32_16x16x32_bf16 v[40:43], v[186:189], v[210:213], v[40:43]
	v_mfma_f32_16x16x32_bf16 v[36:39], v[174:177], v[214:217], v[36:39]
	v_mfma_f32_16x16x32_bf16 v[36:39], v[178:181], v[218:221], v[36:39]
	v_mfma_f32_16x16x32_bf16 v[32:35], v[182:185], v[214:217], v[32:35]
	v_mfma_f32_16x16x32_bf16 v[32:35], v[186:189], v[218:221], v[32:35]
	s_setprio 0
	s_barrier
	s_add_i32 s35, s55, s36
	v_lshl_add_u64 v[222:223], s[26:27], 0, v[130:131]
	s_mov_b32 m0, s35
	v_lshl_add_u64 v[224:225], s[26:27], 0, v[134:135]
	global_load_lds_dwordx4 v[222:223], off
	s_add_i32 m0, s35, 0x2000
	s_add_u32 s58, s26, 0x100000
	s_addc_u32 s59, s27, 0
	s_add_i32 s35, s56, s36
	global_load_lds_dwordx4 v[224:225], off
	v_lshl_add_u64 v[190:191], s[58:59], 0, v[130:131]
	s_mov_b32 m0, s35
	v_lshl_add_u64 v[226:227], s[28:29], 0, v[128:129]
	global_load_lds_dwordx4 v[190:191], off
	v_lshl_add_u64 v[190:191], s[58:59], 0, v[134:135]
	s_add_i32 m0, s35, 0x2000
	v_lshl_add_u64 v[228:229], s[28:29], 0, v[132:133]
	global_load_lds_dwordx4 v[190:191], off
	s_mov_b32 m0, s41
	s_nop 0
	global_load_lds_dwordx4 v[226:227], off
	s_mov_b32 m0, s42
	s_nop 0
	global_load_lds_dwordx4 v[228:229], off
	ds_read_b128 v[190:193], v171 offset:16384
	ds_read_b128 v[194:197], v171 offset:17408
	ds_read_b128 v[198:201], v171 offset:18432
	ds_read_b128 v[202:205], v171 offset:19456
	ds_read_b128 v[206:209], v171 offset:20480
	ds_read_b128 v[210:213], v171 offset:21504
	ds_read_b128 v[214:217], v171 offset:22528
	ds_read_b128 v[218:221], v171 offset:23552
	s_waitcnt vmcnt(8)
	s_waitcnt lgkmcnt(0)
	s_barrier
	s_setprio 1
	s_waitcnt lgkmcnt(0)
	v_mfma_f32_16x16x32_bf16 v[92:95], v[148:151], v[190:193], v[92:95]
	v_mfma_f32_16x16x32_bf16 v[92:95], v[152:155], v[194:197], v[92:95]
	v_mfma_f32_16x16x32_bf16 v[88:91], v[156:159], v[190:193], v[88:91]
	v_mfma_f32_16x16x32_bf16 v[88:91], v[160:163], v[194:197], v[88:91]
	v_mfma_f32_16x16x32_bf16 v[84:87], v[148:151], v[198:201], v[84:87]
	v_mfma_f32_16x16x32_bf16 v[84:87], v[152:155], v[202:205], v[84:87]
	v_mfma_f32_16x16x32_bf16 v[80:83], v[156:159], v[198:201], v[80:83]
	v_mfma_f32_16x16x32_bf16 v[80:83], v[160:163], v[202:205], v[80:83]
	v_mfma_f32_16x16x32_bf16 v[76:79], v[148:151], v[206:209], v[76:79]
	v_mfma_f32_16x16x32_bf16 v[76:79], v[152:155], v[210:213], v[76:79]
	v_mfma_f32_16x16x32_bf16 v[72:75], v[156:159], v[206:209], v[72:75]
	v_mfma_f32_16x16x32_bf16 v[72:75], v[160:163], v[210:213], v[72:75]
	v_mfma_f32_16x16x32_bf16 v[68:71], v[148:151], v[214:217], v[68:71]
	v_mfma_f32_16x16x32_bf16 v[68:71], v[152:155], v[218:221], v[68:71]
	v_mfma_f32_16x16x32_bf16 v[64:67], v[156:159], v[214:217], v[64:67]
	v_mfma_f32_16x16x32_bf16 v[64:67], v[160:163], v[218:221], v[64:67]
	s_setprio 0
	s_setprio 1
	v_mfma_f32_16x16x32_bf16 v[28:31], v[174:177], v[190:193], v[28:31]
	v_mfma_f32_16x16x32_bf16 v[28:31], v[178:181], v[194:197], v[28:31]
	v_mfma_f32_16x16x32_bf16 v[24:27], v[182:185], v[190:193], v[24:27]
	v_mfma_f32_16x16x32_bf16 v[24:27], v[186:189], v[194:197], v[24:27]
	v_mfma_f32_16x16x32_bf16 v[20:23], v[174:177], v[198:201], v[20:23]
	v_mfma_f32_16x16x32_bf16 v[20:23], v[178:181], v[202:205], v[20:23]
	v_mfma_f32_16x16x32_bf16 v[16:19], v[182:185], v[198:201], v[16:19]
	v_mfma_f32_16x16x32_bf16 v[16:19], v[186:189], v[202:205], v[16:19]
	v_mfma_f32_16x16x32_bf16 v[12:15], v[174:177], v[206:209], v[12:15]
	v_mfma_f32_16x16x32_bf16 v[12:15], v[178:181], v[210:213], v[12:15]
	v_mfma_f32_16x16x32_bf16 v[8:11], v[182:185], v[206:209], v[8:11]
	v_mfma_f32_16x16x32_bf16 v[8:11], v[186:189], v[210:213], v[8:11]
	v_mfma_f32_16x16x32_bf16 v[4:7], v[174:177], v[214:217], v[4:7]
	v_mfma_f32_16x16x32_bf16 v[4:7], v[178:181], v[218:221], v[4:7]
	v_mfma_f32_16x16x32_bf16 v[0:3], v[182:185], v[214:217], v[0:3]
	v_mfma_f32_16x16x32_bf16 v[0:3], v[186:189], v[218:221], v[0:3]
	s_setprio 0
	s_barrier
	s_add_i32 s35, 0, 0x18000
	v_add_u32_e32 v136, s35, v165
	s_add_i32 s57, 0, 0x1c000
	ds_read_b128 v[148:151], v136
	ds_read_b128 v[152:155], v136 offset:1024
	ds_read_b128 v[156:159], v136 offset:2048
	ds_read_b128 v[160:163], v136 offset:3072
	v_add_u32_e32 v136, s57, v165
	ds_read_b128 v[174:177], v136
	ds_read_b128 v[178:181], v136 offset:1024
	ds_read_b128 v[182:185], v136 offset:2048
	ds_read_b128 v[186:189], v136 offset:3072
	s_add_u32 s28, s28, 0x100000
	s_addc_u32 s29, s29, 0
	s_mov_b32 m0, s43
	v_lshl_add_u64 v[190:191], s[28:29], 0, v[128:129]
	global_load_lds_dwordx4 v[190:191], off
	v_lshl_add_u64 v[190:191], s[28:29], 0, v[132:133]
	s_mov_b32 m0, s44
	s_nop 0
	global_load_lds_dwordx4 v[190:191], off
	ds_read_b128 v[190:193], v171 offset:32768
	ds_read_b128 v[194:197], v171 offset:33792
	ds_read_b128 v[198:201], v171 offset:34816
	ds_read_b128 v[202:205], v171 offset:35840
	ds_read_b128 v[206:209], v171 offset:36864
	ds_read_b128 v[210:213], v171 offset:37888
	ds_read_b128 v[214:217], v171 offset:38912
	ds_read_b128 v[218:221], v171 offset:39936
	s_waitcnt vmcnt(8)
	s_waitcnt lgkmcnt(0)
	s_barrier
	s_setprio 1
	s_waitcnt lgkmcnt(0)
	v_mfma_f32_16x16x32_bf16 v[124:127], v[148:151], v[190:193], v[124:127]
	v_mfma_f32_16x16x32_bf16 v[124:127], v[152:155], v[194:197], v[124:127]
	v_mfma_f32_16x16x32_bf16 v[120:123], v[156:159], v[190:193], v[120:123]
	v_mfma_f32_16x16x32_bf16 v[120:123], v[160:163], v[194:197], v[120:123]
	v_mfma_f32_16x16x32_bf16 v[116:119], v[148:151], v[198:201], v[116:119]
	v_mfma_f32_16x16x32_bf16 v[116:119], v[152:155], v[202:205], v[116:119]
	v_mfma_f32_16x16x32_bf16 v[112:115], v[156:159], v[198:201], v[112:115]
	v_mfma_f32_16x16x32_bf16 v[112:115], v[160:163], v[202:205], v[112:115]
	v_mfma_f32_16x16x32_bf16 v[108:111], v[148:151], v[206:209], v[108:111]
	v_mfma_f32_16x16x32_bf16 v[108:111], v[152:155], v[210:213], v[108:111]
	v_mfma_f32_16x16x32_bf16 v[104:107], v[156:159], v[206:209], v[104:107]
	v_mfma_f32_16x16x32_bf16 v[104:107], v[160:163], v[210:213], v[104:107]
	v_mfma_f32_16x16x32_bf16 v[100:103], v[148:151], v[214:217], v[100:103]
	v_mfma_f32_16x16x32_bf16 v[100:103], v[152:155], v[218:221], v[100:103]
	v_mfma_f32_16x16x32_bf16 v[96:99], v[156:159], v[214:217], v[96:99]
	v_mfma_f32_16x16x32_bf16 v[96:99], v[160:163], v[218:221], v[96:99]
	s_setprio 0
	s_setprio 1
	v_mfma_f32_16x16x32_bf16 v[60:63], v[174:177], v[190:193], v[60:63]
	v_mfma_f32_16x16x32_bf16 v[60:63], v[178:181], v[194:197], v[60:63]
	v_mfma_f32_16x16x32_bf16 v[56:59], v[182:185], v[190:193], v[56:59]
	v_mfma_f32_16x16x32_bf16 v[56:59], v[186:189], v[194:197], v[56:59]
	v_mfma_f32_16x16x32_bf16 v[52:55], v[174:177], v[198:201], v[52:55]
	v_mfma_f32_16x16x32_bf16 v[52:55], v[178:181], v[202:205], v[52:55]
	v_mfma_f32_16x16x32_bf16 v[48:51], v[182:185], v[198:201], v[48:51]
	v_mfma_f32_16x16x32_bf16 v[48:51], v[186:189], v[202:205], v[48:51]
	v_mfma_f32_16x16x32_bf16 v[44:47], v[174:177], v[206:209], v[44:47]
	v_mfma_f32_16x16x32_bf16 v[44:47], v[178:181], v[210:213], v[44:47]
	v_mfma_f32_16x16x32_bf16 v[40:43], v[182:185], v[206:209], v[40:43]
	v_mfma_f32_16x16x32_bf16 v[40:43], v[186:189], v[210:213], v[40:43]
	v_mfma_f32_16x16x32_bf16 v[36:39], v[174:177], v[214:217], v[36:39]
	v_mfma_f32_16x16x32_bf16 v[36:39], v[178:181], v[218:221], v[36:39]
	v_mfma_f32_16x16x32_bf16 v[32:35], v[182:185], v[214:217], v[32:35]
	v_mfma_f32_16x16x32_bf16 v[32:35], v[186:189], v[218:221], v[32:35]
	s_setprio 0
	s_barrier
	s_add_i32 s28, s35, s36
	v_lshl_add_u64 v[190:191], v[222:223], 0, s[12:13]
	s_mov_b32 m0, s28
	s_nop 0
	global_load_lds_dwordx4 v[190:191], off
	s_add_i32 m0, s28, 0x2000
	s_add_u32 s26, s26, 0x100800
	v_lshl_add_u64 v[190:191], v[224:225], 0, s[12:13]
	s_addc_u32 s27, s27, 0
	s_add_i32 s28, s57, s36
	global_load_lds_dwordx4 v[190:191], off
	v_lshl_add_u64 v[190:191], s[26:27], 0, v[130:131]
	s_mov_b32 m0, s28
	s_nop 0
	global_load_lds_dwordx4 v[190:191], off
	v_lshl_add_u64 v[190:191], s[26:27], 0, v[134:135]
	s_add_i32 m0, s28, 0x2000
	s_nop 0
	global_load_lds_dwordx4 v[190:191], off
	v_lshl_add_u64 v[190:191], v[226:227], 0, s[12:13]
	s_mov_b32 m0, s49
	s_nop 0
	global_load_lds_dwordx4 v[190:191], off
	v_lshl_add_u64 v[190:191], v[228:229], 0, s[12:13]
	s_mov_b32 m0, s50
	s_nop 0
	global_load_lds_dwordx4 v[190:191], off
	ds_read_b128 v[190:193], v171 offset:49152
	ds_read_b128 v[194:197], v171 offset:50176
	ds_read_b128 v[198:201], v171 offset:51200
	ds_read_b128 v[202:205], v171 offset:52224
	ds_read_b128 v[206:209], v171 offset:53248
	ds_read_b128 v[210:213], v171 offset:54272
	ds_read_b128 v[214:217], v171 offset:55296
	ds_read_b128 v[218:221], v171 offset:56320
	s_waitcnt vmcnt(8)
	s_waitcnt lgkmcnt(0)
	s_barrier
	s_setprio 1
	s_waitcnt lgkmcnt(0)
	v_mfma_f32_16x16x32_bf16 v[92:95], v[148:151], v[190:193], v[92:95]
	v_mfma_f32_16x16x32_bf16 v[92:95], v[152:155], v[194:197], v[92:95]
	v_mfma_f32_16x16x32_bf16 v[88:91], v[156:159], v[190:193], v[88:91]
	v_mfma_f32_16x16x32_bf16 v[88:91], v[160:163], v[194:197], v[88:91]
	v_mfma_f32_16x16x32_bf16 v[84:87], v[148:151], v[198:201], v[84:87]
	v_mfma_f32_16x16x32_bf16 v[84:87], v[152:155], v[202:205], v[84:87]
	v_mfma_f32_16x16x32_bf16 v[80:83], v[156:159], v[198:201], v[80:83]
	v_mfma_f32_16x16x32_bf16 v[80:83], v[160:163], v[202:205], v[80:83]
	v_mfma_f32_16x16x32_bf16 v[76:79], v[148:151], v[206:209], v[76:79]
	v_mfma_f32_16x16x32_bf16 v[76:79], v[152:155], v[210:213], v[76:79]
	v_mfma_f32_16x16x32_bf16 v[72:75], v[156:159], v[206:209], v[72:75]
	v_mfma_f32_16x16x32_bf16 v[72:75], v[160:163], v[210:213], v[72:75]
	v_mfma_f32_16x16x32_bf16 v[68:71], v[148:151], v[214:217], v[68:71]
	v_mfma_f32_16x16x32_bf16 v[68:71], v[152:155], v[218:221], v[68:71]
	v_mfma_f32_16x16x32_bf16 v[64:67], v[156:159], v[214:217], v[64:67]
	v_mfma_f32_16x16x32_bf16 v[64:67], v[160:163], v[218:221], v[64:67]
	s_setprio 0
	s_setprio 1
	v_mfma_f32_16x16x32_bf16 v[28:31], v[174:177], v[190:193], v[28:31]
	v_mfma_f32_16x16x32_bf16 v[28:31], v[178:181], v[194:197], v[28:31]
	v_mfma_f32_16x16x32_bf16 v[24:27], v[182:185], v[190:193], v[24:27]
	v_mfma_f32_16x16x32_bf16 v[24:27], v[186:189], v[194:197], v[24:27]
	v_mfma_f32_16x16x32_bf16 v[20:23], v[174:177], v[198:201], v[20:23]
	v_mfma_f32_16x16x32_bf16 v[20:23], v[178:181], v[202:205], v[20:23]
	v_mfma_f32_16x16x32_bf16 v[16:19], v[182:185], v[198:201], v[16:19]
	v_mfma_f32_16x16x32_bf16 v[16:19], v[186:189], v[202:205], v[16:19]
	v_mfma_f32_16x16x32_bf16 v[12:15], v[174:177], v[206:209], v[12:15]
	v_mfma_f32_16x16x32_bf16 v[12:15], v[178:181], v[210:213], v[12:15]
	v_mfma_f32_16x16x32_bf16 v[8:11], v[182:185], v[206:209], v[8:11]
	v_mfma_f32_16x16x32_bf16 v[8:11], v[186:189], v[210:213], v[8:11]
	v_mfma_f32_16x16x32_bf16 v[4:7], v[174:177], v[214:217], v[4:7]
	v_mfma_f32_16x16x32_bf16 v[4:7], v[178:181], v[218:221], v[4:7]
	v_mfma_f32_16x16x32_bf16 v[0:3], v[182:185], v[214:217], v[0:3]
	v_mfma_f32_16x16x32_bf16 v[0:3], v[186:189], v[218:221], v[0:3]
	s_setprio 0
	s_barrier
	s_add_i32 s34, s34, 2
	s_add_u32 s6, s6, 0x1000
	s_addc_u32 s7, s7, 0
	s_add_u32 s30, s30, 0x1000
	s_addc_u32 s31, s31, 0
	s_cmp_gt_u32 s34, 61
	s_cbranch_scc0 .LBB0_200
	s_and_b64 vcc, exec, s[0:1]
	s_cbranch_vccz .LBB0_203
	s_barrier

.LBB0_333:
	ds_read_b128 v[144:147], v152
	ds_read_b128 v[156:159], v152 offset:1024
	ds_read_b128 v[160:163], v152 offset:2048
	ds_read_b128 v[164:167], v152 offset:3072
	ds_read_b128 v[168:171], v153
	ds_read_b128 v[172:175], v153 offset:1024
	ds_read_b128 v[176:179], v153 offset:2048
	ds_read_b128 v[180:183], v153 offset:3072
	s_add_u32 s28, s24, 0x100
	s_addc_u32 s29, s25, 0
	s_cmp_eq_u32 s56, 60
	s_cselect_b32 s35, s13, s29
	s_cselect_b32 s34, s52, s28
	s_cselect_b32 s31, s11, s55
	s_cselect_b32 s30, s53, s54
	v_lshl_add_u64 v[184:185], s[24:25], 0, v[136:137]
	s_add_i32 m0, s21, 0xc000
	s_nop 0
	global_load_lds_dwordx4 v[184:185], off
	v_lshl_add_u64 v[184:185], s[24:25], 0, v[138:139]
	s_add_i32 m0, s21, 0xe000
	s_nop 0
	global_load_lds_dwordx4 v[184:185], off
	ds_read_b128 v[184:187], v154
	ds_read_b128 v[188:191], v154 offset:1024
	ds_read_b128 v[192:195], v154 offset:2048
	ds_read_b128 v[196:199], v154 offset:3072
	ds_read_b128 v[200:203], v154 offset:4096
	ds_read_b128 v[204:207], v154 offset:5120
	ds_read_b128 v[208:211], v154 offset:6144
	ds_read_b128 v[212:215], v154 offset:7168
	s_waitcnt vmcnt(8)
	s_waitcnt lgkmcnt(0)
	s_barrier
	s_setprio 1
	s_waitcnt lgkmcnt(0)
	v_mfma_f32_16x16x32_bf16 v[124:127], v[144:147], v[184:187], v[124:127]
	v_mfma_f32_16x16x32_bf16 v[124:127], v[156:159], v[188:191], v[124:127]
	v_mfma_f32_16x16x32_bf16 v[120:123], v[160:163], v[184:187], v[120:123]
	v_mfma_f32_16x16x32_bf16 v[120:123], v[164:167], v[188:191], v[120:123]
	v_mfma_f32_16x16x32_bf16 v[116:119], v[144:147], v[192:195], v[116:119]
	v_mfma_f32_16x16x32_bf16 v[116:119], v[156:159], v[196:199], v[116:119]
	v_mfma_f32_16x16x32_bf16 v[108:111], v[160:163], v[192:195], v[108:111]
	v_mfma_f32_16x16x32_bf16 v[108:111], v[164:167], v[196:199], v[108:111]
	v_mfma_f32_16x16x32_bf16 v[100:103], v[144:147], v[200:203], v[100:103]
	v_mfma_f32_16x16x32_bf16 v[100:103], v[156:159], v[204:207], v[100:103]
	v_mfma_f32_16x16x32_bf16 v[92:95], v[160:163], v[200:203], v[92:95]
	v_mfma_f32_16x16x32_bf16 v[92:95], v[164:167], v[204:207], v[92:95]
	v_mfma_f32_16x16x32_bf16 v[84:87], v[144:147], v[208:211], v[84:87]
	v_mfma_f32_16x16x32_bf16 v[84:87], v[156:159], v[212:215], v[84:87]
	v_mfma_f32_16x16x32_bf16 v[76:79], v[160:163], v[208:211], v[76:79]
	v_mfma_f32_16x16x32_bf16 v[76:79], v[164:167], v[212:215], v[76:79]
	s_setprio 0
	s_setprio 1
	v_mfma_f32_16x16x32_bf16 v[112:115], v[168:171], v[184:187], v[112:115]
	v_mfma_f32_16x16x32_bf16 v[112:115], v[172:175], v[188:191], v[112:115]
	v_mfma_f32_16x16x32_bf16 v[104:107], v[176:179], v[184:187], v[104:107]
	v_mfma_f32_16x16x32_bf16 v[104:107], v[180:183], v[188:191], v[104:107]
	v_mfma_f32_16x16x32_bf16 v[96:99], v[168:171], v[192:195], v[96:99]
	v_mfma_f32_16x16x32_bf16 v[96:99], v[172:175], v[196:199], v[96:99]
	v_mfma_f32_16x16x32_bf16 v[88:91], v[176:179], v[192:195], v[88:91]
	v_mfma_f32_16x16x32_bf16 v[88:91], v[180:183], v[196:199], v[88:91]
	v_mfma_f32_16x16x32_bf16 v[80:83], v[168:171], v[200:203], v[80:83]
	v_mfma_f32_16x16x32_bf16 v[80:83], v[172:175], v[204:207], v[80:83]
	v_mfma_f32_16x16x32_bf16 v[72:75], v[176:179], v[200:203], v[72:75]
	v_mfma_f32_16x16x32_bf16 v[72:75], v[180:183], v[204:207], v[72:75]
	v_mfma_f32_16x16x32_bf16 v[68:71], v[168:171], v[208:211], v[68:71]
	v_mfma_f32_16x16x32_bf16 v[68:71], v[172:175], v[212:215], v[68:71]
	v_mfma_f32_16x16x32_bf16 v[64:67], v[176:179], v[208:211], v[64:67]
	v_mfma_f32_16x16x32_bf16 v[64:67], v[180:183], v[212:215], v[64:67]
	s_setprio 0
	s_barrier
	s_add_i32 s24, s49, s41
	v_lshl_add_u64 v[216:217], s[30:31], 0, v[130:131]
	s_mov_b32 m0, s24
	v_lshl_add_u64 v[218:219], s[30:31], 0, v[134:135]
	global_load_lds_dwordx4 v[216:217], off
	s_add_i32 m0, s24, 0x2000
	s_add_u32 s24, s30, 0x100000
	s_addc_u32 s25, s31, 0
	s_add_i32 s57, s50, s41
	global_load_lds_dwordx4 v[218:219], off
	v_lshl_add_u64 v[184:185], s[24:25], 0, v[130:131]
	s_mov_b32 m0, s57
	v_lshl_add_u64 v[220:221], s[34:35], 0, v[128:129]
	global_load_lds_dwordx4 v[184:185], off
	v_lshl_add_u64 v[184:185], s[24:25], 0, v[134:135]
	s_add_i32 m0, s57, 0x2000
	v_lshl_add_u64 v[222:223], s[34:35], 0, v[132:133]
	global_load_lds_dwordx4 v[184:185], off
	s_mov_b32 m0, s21
	s_nop 0
	global_load_lds_dwordx4 v[220:221], off
	s_mov_b32 m0, s42
	s_nop 0
	global_load_lds_dwordx4 v[222:223], off
	ds_read_b128 v[184:187], v154 offset:16384
	ds_read_b128 v[188:191], v154 offset:17408
	ds_read_b128 v[192:195], v154 offset:18432
	ds_read_b128 v[196:199], v154 offset:19456
	ds_read_b128 v[200:203], v154 offset:20480
	ds_read_b128 v[204:207], v154 offset:21504
	ds_read_b128 v[208:211], v154 offset:22528
	ds_read_b128 v[212:215], v154 offset:23552
	s_waitcnt vmcnt(8)
	s_waitcnt lgkmcnt(0)
	s_barrier
	s_setprio 1
	s_waitcnt lgkmcnt(0)
	v_mfma_f32_16x16x32_bf16 v[60:63], v[144:147], v[184:187], v[60:63]
	v_mfma_f32_16x16x32_bf16 v[60:63], v[156:159], v[188:191], v[60:63]
	v_mfma_f32_16x16x32_bf16 v[56:59], v[160:163], v[184:187], v[56:59]
	v_mfma_f32_16x16x32_bf16 v[56:59], v[164:167], v[188:191], v[56:59]
	v_mfma_f32_16x16x32_bf16 v[52:55], v[144:147], v[192:195], v[52:55]
	v_mfma_f32_16x16x32_bf16 v[52:55], v[156:159], v[196:199], v[52:55]
	v_mfma_f32_16x16x32_bf16 v[44:47], v[160:163], v[192:195], v[44:47]
	v_mfma_f32_16x16x32_bf16 v[44:47], v[164:167], v[196:199], v[44:47]
	v_mfma_f32_16x16x32_bf16 v[36:39], v[144:147], v[200:203], v[36:39]
	v_mfma_f32_16x16x32_bf16 v[36:39], v[156:159], v[204:207], v[36:39]
	v_mfma_f32_16x16x32_bf16 v[28:31], v[160:163], v[200:203], v[28:31]
	v_mfma_f32_16x16x32_bf16 v[28:31], v[164:167], v[204:207], v[28:31]
	v_mfma_f32_16x16x32_bf16 v[20:23], v[144:147], v[208:211], v[20:23]
	v_mfma_f32_16x16x32_bf16 v[20:23], v[156:159], v[212:215], v[20:23]
	v_mfma_f32_16x16x32_bf16 v[12:15], v[160:163], v[208:211], v[12:15]
	v_mfma_f32_16x16x32_bf16 v[12:15], v[164:167], v[212:215], v[12:15]
	s_setprio 0
	s_setprio 1
	v_mfma_f32_16x16x32_bf16 v[48:51], v[168:171], v[184:187], v[48:51]
	v_mfma_f32_16x16x32_bf16 v[48:51], v[172:175], v[188:191], v[48:51]
	v_mfma_f32_16x16x32_bf16 v[40:43], v[176:179], v[184:187], v[40:43]
	v_mfma_f32_16x16x32_bf16 v[40:43], v[180:183], v[188:191], v[40:43]
	v_mfma_f32_16x16x32_bf16 v[32:35], v[168:171], v[192:195], v[32:35]
	v_mfma_f32_16x16x32_bf16 v[32:35], v[172:175], v[196:199], v[32:35]
	v_mfma_f32_16x16x32_bf16 v[24:27], v[176:179], v[192:195], v[24:27]
	v_mfma_f32_16x16x32_bf16 v[24:27], v[180:183], v[196:199], v[24:27]
	v_mfma_f32_16x16x32_bf16 v[16:19], v[168:171], v[200:203], v[16:19]
	v_mfma_f32_16x16x32_bf16 v[16:19], v[172:175], v[204:207], v[16:19]
	v_mfma_f32_16x16x32_bf16 v[8:11], v[176:179], v[200:203], v[8:11]
	v_mfma_f32_16x16x32_bf16 v[8:11], v[180:183], v[204:207], v[8:11]
	v_mfma_f32_16x16x32_bf16 v[4:7], v[168:171], v[208:211], v[4:7]
	v_mfma_f32_16x16x32_bf16 v[4:7], v[172:175], v[212:215], v[4:7]
	v_mfma_f32_16x16x32_bf16 v[0:3], v[176:179], v[208:211], v[0:3]
	v_mfma_f32_16x16x32_bf16 v[0:3], v[180:183], v[212:215], v[0:3]
	s_setprio 0
	s_barrier
	s_add_i32 s57, 0, 0x18000
	v_add_u32_e32 v155, s57, v149
	s_add_i32 s58, 0, 0x1c000
	ds_read_b128 v[144:147], v155
	ds_read_b128 v[156:159], v155 offset:1024
	ds_read_b128 v[160:163], v155 offset:2048
	ds_read_b128 v[164:167], v155 offset:3072
	v_add_u32_e32 v155, s58, v149
	ds_read_b128 v[168:171], v155
	ds_read_b128 v[172:175], v155 offset:1024
	ds_read_b128 v[176:179], v155 offset:2048
	ds_read_b128 v[180:183], v155 offset:3072
	s_add_u32 s24, s34, 0x100000
	s_addc_u32 s25, s35, 0
	s_mov_b32 m0, s43
	v_lshl_add_u64 v[184:185], s[24:25], 0, v[128:129]
	global_load_lds_dwordx4 v[184:185], off
	v_lshl_add_u64 v[184:185], s[24:25], 0, v[132:133]
	s_mov_b32 m0, s44
	s_nop 0
	global_load_lds_dwordx4 v[184:185], off
	ds_read_b128 v[184:187], v154 offset:32768
	ds_read_b128 v[188:191], v154 offset:33792
	ds_read_b128 v[192:195], v154 offset:34816
	ds_read_b128 v[196:199], v154 offset:35840
	ds_read_b128 v[200:203], v154 offset:36864
	ds_read_b128 v[204:207], v154 offset:37888
	ds_read_b128 v[208:211], v154 offset:38912
	ds_read_b128 v[212:215], v154 offset:39936
	s_waitcnt vmcnt(8)
	s_waitcnt lgkmcnt(0)
	s_barrier
	s_setprio 1
	s_waitcnt lgkmcnt(0)
	v_mfma_f32_16x16x32_bf16 v[124:127], v[144:147], v[184:187], v[124:127]
	v_mfma_f32_16x16x32_bf16 v[124:127], v[156:159], v[188:191], v[124:127]
	v_mfma_f32_16x16x32_bf16 v[120:123], v[160:163], v[184:187], v[120:123]
	v_mfma_f32_16x16x32_bf16 v[120:123], v[164:167], v[188:191], v[120:123]
	v_mfma_f32_16x16x32_bf16 v[116:119], v[144:147], v[192:195], v[116:119]
	v_mfma_f32_16x16x32_bf16 v[116:119], v[156:159], v[196:199], v[116:119]
	v_mfma_f32_16x16x32_bf16 v[108:111], v[160:163], v[192:195], v[108:111]
	v_mfma_f32_16x16x32_bf16 v[108:111], v[164:167], v[196:199], v[108:111]
	v_mfma_f32_16x16x32_bf16 v[100:103], v[144:147], v[200:203], v[100:103]
	v_mfma_f32_16x16x32_bf16 v[100:103], v[156:159], v[204:207], v[100:103]
	v_mfma_f32_16x16x32_bf16 v[92:95], v[160:163], v[200:203], v[92:95]
	v_mfma_f32_16x16x32_bf16 v[92:95], v[164:167], v[204:207], v[92:95]
	v_mfma_f32_16x16x32_bf16 v[84:87], v[144:147], v[208:211], v[84:87]
	v_mfma_f32_16x16x32_bf16 v[84:87], v[156:159], v[212:215], v[84:87]
	v_mfma_f32_16x16x32_bf16 v[76:79], v[160:163], v[208:211], v[76:79]
	v_mfma_f32_16x16x32_bf16 v[76:79], v[164:167], v[212:215], v[76:79]
	s_setprio 0
	s_setprio 1
	v_mfma_f32_16x16x32_bf16 v[112:115], v[168:171], v[184:187], v[112:115]
	v_mfma_f32_16x16x32_bf16 v[112:115], v[172:175], v[188:191], v[112:115]
	v_mfma_f32_16x16x32_bf16 v[104:107], v[176:179], v[184:187], v[104:107]
	v_mfma_f32_16x16x32_bf16 v[104:107], v[180:183], v[188:191], v[104:107]
	v_mfma_f32_16x16x32_bf16 v[96:99], v[168:171], v[192:195], v[96:99]
	v_mfma_f32_16x16x32_bf16 v[96:99], v[172:175], v[196:199], v[96:99]
	v_mfma_f32_16x16x32_bf16 v[88:91], v[176:179], v[192:195], v[88:91]
	v_mfma_f32_16x16x32_bf16 v[88:91], v[180:183], v[196:199], v[88:91]
	v_mfma_f32_16x16x32_bf16 v[80:83], v[168:171], v[200:203], v[80:83]
	v_mfma_f32_16x16x32_bf16 v[80:83], v[172:175], v[204:207], v[80:83]
	v_mfma_f32_16x16x32_bf16 v[72:75], v[176:179], v[200:203], v[72:75]
	v_mfma_f32_16x16x32_bf16 v[72:75], v[180:183], v[204:207], v[72:75]
	v_mfma_f32_16x16x32_bf16 v[68:71], v[168:171], v[208:211], v[68:71]
	v_mfma_f32_16x16x32_bf16 v[68:71], v[172:175], v[212:215], v[68:71]
	v_mfma_f32_16x16x32_bf16 v[64:67], v[176:179], v[208:211], v[64:67]
	v_mfma_f32_16x16x32_bf16 v[64:67], v[180:183], v[212:215], v[64:67]
	s_setprio 0
	s_barrier
	s_add_i32 s24, s57, s41
	v_lshl_add_u64 v[184:185], v[216:217], 0, s[8:9]
	s_mov_b32 m0, s24
	s_nop 0
	global_load_lds_dwordx4 v[184:185], off
	s_add_i32 m0, s24, 0x2000
	s_add_u32 s24, s30, 0x100080
	v_lshl_add_u64 v[184:185], v[218:219], 0, s[8:9]
	s_addc_u32 s25, s31, 0
	s_add_i32 s30, s58, s41
	global_load_lds_dwordx4 v[184:185], off
	v_lshl_add_u64 v[184:185], s[24:25], 0, v[130:131]
	s_mov_b32 m0, s30
	s_nop 0
	global_load_lds_dwordx4 v[184:185], off
	v_lshl_add_u64 v[184:185], s[24:25], 0, v[134:135]
	s_add_i32 m0, s30, 0x2000
	s_nop 0
	global_load_lds_dwordx4 v[184:185], off
	v_lshl_add_u64 v[184:185], v[220:221], 0, s[8:9]
	s_mov_b32 m0, s46
	s_nop 0
	global_load_lds_dwordx4 v[184:185], off
	v_lshl_add_u64 v[184:185], v[222:223], 0, s[8:9]
	s_mov_b32 m0, s47
	s_nop 0
	global_load_lds_dwordx4 v[184:185], off
	ds_read_b128 v[184:187], v154 offset:49152
	ds_read_b128 v[188:191], v154 offset:50176
	ds_read_b128 v[192:195], v154 offset:51200
	ds_read_b128 v[196:199], v154 offset:52224
	ds_read_b128 v[200:203], v154 offset:53248
	ds_read_b128 v[204:207], v154 offset:54272
	ds_read_b128 v[208:211], v154 offset:55296
	ds_read_b128 v[212:215], v154 offset:56320
	s_waitcnt vmcnt(8)
	s_waitcnt lgkmcnt(0)
	s_barrier
	s_setprio 1
	s_waitcnt lgkmcnt(0)
	v_mfma_f32_16x16x32_bf16 v[60:63], v[144:147], v[184:187], v[60:63]
	v_mfma_f32_16x16x32_bf16 v[60:63], v[156:159], v[188:191], v[60:63]
	v_mfma_f32_16x16x32_bf16 v[56:59], v[160:163], v[184:187], v[56:59]
	v_mfma_f32_16x16x32_bf16 v[56:59], v[164:167], v[188:191], v[56:59]
	v_mfma_f32_16x16x32_bf16 v[52:55], v[144:147], v[192:195], v[52:55]
	v_mfma_f32_16x16x32_bf16 v[52:55], v[156:159], v[196:199], v[52:55]
	v_mfma_f32_16x16x32_bf16 v[44:47], v[160:163], v[192:195], v[44:47]
	v_mfma_f32_16x16x32_bf16 v[44:47], v[164:167], v[196:199], v[44:47]
	v_mfma_f32_16x16x32_bf16 v[36:39], v[144:147], v[200:203], v[36:39]
	v_mfma_f32_16x16x32_bf16 v[36:39], v[156:159], v[204:207], v[36:39]
	v_mfma_f32_16x16x32_bf16 v[28:31], v[160:163], v[200:203], v[28:31]
	v_mfma_f32_16x16x32_bf16 v[28:31], v[164:167], v[204:207], v[28:31]
	v_mfma_f32_16x16x32_bf16 v[20:23], v[144:147], v[208:211], v[20:23]
	v_mfma_f32_16x16x32_bf16 v[20:23], v[156:159], v[212:215], v[20:23]
	v_mfma_f32_16x16x32_bf16 v[12:15], v[160:163], v[208:211], v[12:15]
	v_mfma_f32_16x16x32_bf16 v[12:15], v[164:167], v[212:215], v[12:15]
	s_setprio 0
	s_setprio 1
	v_mfma_f32_16x16x32_bf16 v[48:51], v[168:171], v[184:187], v[48:51]
	v_mfma_f32_16x16x32_bf16 v[48:51], v[172:175], v[188:191], v[48:51]
	v_mfma_f32_16x16x32_bf16 v[40:43], v[176:179], v[184:187], v[40:43]
	v_mfma_f32_16x16x32_bf16 v[40:43], v[180:183], v[188:191], v[40:43]
	v_mfma_f32_16x16x32_bf16 v[32:35], v[168:171], v[192:195], v[32:35]
	v_mfma_f32_16x16x32_bf16 v[32:35], v[172:175], v[196:199], v[32:35]
	v_mfma_f32_16x16x32_bf16 v[24:27], v[176:179], v[192:195], v[24:27]
	v_mfma_f32_16x16x32_bf16 v[24:27], v[180:183], v[196:199], v[24:27]
	v_mfma_f32_16x16x32_bf16 v[16:19], v[168:171], v[200:203], v[16:19]
	v_mfma_f32_16x16x32_bf16 v[16:19], v[172:175], v[204:207], v[16:19]
	v_mfma_f32_16x16x32_bf16 v[8:11], v[176:179], v[200:203], v[8:11]
	v_mfma_f32_16x16x32_bf16 v[8:11], v[180:183], v[204:207], v[8:11]
	v_mfma_f32_16x16x32_bf16 v[4:7], v[168:171], v[208:211], v[4:7]
	v_mfma_f32_16x16x32_bf16 v[4:7], v[172:175], v[212:215], v[4:7]
	v_mfma_f32_16x16x32_bf16 v[0:3], v[176:179], v[208:211], v[0:3]
	v_mfma_f32_16x16x32_bf16 v[0:3], v[180:183], v[212:215], v[0:3]
	s_setprio 0
	s_barrier
	s_add_i32 s56, s56, 2
	s_add_u32 s54, s54, 0x100
	s_addc_u32 s55, s55, 0
	s_cmp_gt_u32 s56, 61
	s_mov_b64 s[24:25], s[28:29]
	s_cbranch_scc0 .LBB0_333
	s_and_b64 vcc, exec, s[0:1]
	s_cbranch_vccz .LBB0_336
	s_barrier

.LBB0_1202:
	ds_read_b128 v[128:131], v176
	ds_read_b128 v[132:135], v176 offset:1024
	ds_read_b128 v[136:139], v176 offset:2048
	ds_read_b128 v[140:143], v176 offset:3072
	ds_read_b128 v[144:147], v177
	ds_read_b128 v[148:151], v177 offset:1024
	ds_read_b128 v[180:183], v177 offset:2048
	ds_read_b128 v[184:187], v177 offset:3072
	s_add_u32 s30, s28, 0xfff00080
	s_addc_u32 s31, s29, -1
	s_cmp_eq_u32 s40, 60
	s_cselect_b32 s35, s23, s31
	s_cselect_b32 s34, s36, s30
	s_cselect_b32 s31, s21, s39
	s_cselect_b32 s30, s37, s38
	v_lshl_add_u64 v[172:173], s[28:29], 0, v[164:165]
	s_add_i32 m0, s7, 0xc000
	s_nop 0
	global_load_lds_dwordx4 v[172:173], off
	v_lshl_add_u64 v[172:173], s[28:29], 0, v[166:167]
	s_add_i32 m0, s7, 0xe000
	s_nop 0
	global_load_lds_dwordx4 v[172:173], off
	ds_read_b128 v[188:191], v178
	ds_read_b128 v[192:195], v178 offset:1024
	ds_read_b128 v[196:199], v178 offset:2048
	ds_read_b128 v[200:203], v178 offset:3072
	ds_read_b128 v[204:207], v178 offset:4096
	ds_read_b128 v[208:211], v178 offset:5120
	ds_read_b128 v[212:215], v178 offset:6144
	ds_read_b128 v[216:219], v178 offset:7168
	s_waitcnt vmcnt(8)
	s_waitcnt lgkmcnt(0)
	s_barrier
	s_setprio 1
	s_waitcnt lgkmcnt(0)
	v_mfma_f32_16x16x32_bf16 v[124:127], v[128:131], v[188:191], v[124:127]
	v_mfma_f32_16x16x32_bf16 v[124:127], v[132:135], v[192:195], v[124:127]
	v_mfma_f32_16x16x32_bf16 v[120:123], v[136:139], v[188:191], v[120:123]
	v_mfma_f32_16x16x32_bf16 v[120:123], v[140:143], v[192:195], v[120:123]
	v_mfma_f32_16x16x32_bf16 v[108:111], v[128:131], v[196:199], v[108:111]
	v_mfma_f32_16x16x32_bf16 v[108:111], v[132:135], v[200:203], v[108:111]
	v_mfma_f32_16x16x32_bf16 v[104:107], v[136:139], v[196:199], v[104:107]
	v_mfma_f32_16x16x32_bf16 v[104:107], v[140:143], v[200:203], v[104:107]
	v_mfma_f32_16x16x32_bf16 v[92:95], v[128:131], v[204:207], v[92:95]
	v_mfma_f32_16x16x32_bf16 v[92:95], v[132:135], v[208:211], v[92:95]
	v_mfma_f32_16x16x32_bf16 v[88:91], v[136:139], v[204:207], v[88:91]
	v_mfma_f32_16x16x32_bf16 v[88:91], v[140:143], v[208:211], v[88:91]
	v_mfma_f32_16x16x32_bf16 v[76:79], v[128:131], v[212:215], v[76:79]
	v_mfma_f32_16x16x32_bf16 v[76:79], v[132:135], v[216:219], v[76:79]
	v_mfma_f32_16x16x32_bf16 v[72:75], v[136:139], v[212:215], v[72:75]
	v_mfma_f32_16x16x32_bf16 v[72:75], v[140:143], v[216:219], v[72:75]
	s_setprio 0
	s_setprio 1
	v_mfma_f32_16x16x32_bf16 v[116:119], v[144:147], v[188:191], v[116:119]
	v_mfma_f32_16x16x32_bf16 v[116:119], v[148:151], v[192:195], v[116:119]
	v_mfma_f32_16x16x32_bf16 v[112:115], v[180:183], v[188:191], v[112:115]
	v_mfma_f32_16x16x32_bf16 v[112:115], v[184:187], v[192:195], v[112:115]
	v_mfma_f32_16x16x32_bf16 v[100:103], v[144:147], v[196:199], v[100:103]
	v_mfma_f32_16x16x32_bf16 v[100:103], v[148:151], v[200:203], v[100:103]
	v_mfma_f32_16x16x32_bf16 v[96:99], v[180:183], v[196:199], v[96:99]
	v_mfma_f32_16x16x32_bf16 v[96:99], v[184:187], v[200:203], v[96:99]
	v_mfma_f32_16x16x32_bf16 v[84:87], v[144:147], v[204:207], v[84:87]
	v_mfma_f32_16x16x32_bf16 v[84:87], v[148:151], v[208:211], v[84:87]
	v_mfma_f32_16x16x32_bf16 v[80:83], v[180:183], v[204:207], v[80:83]
	v_mfma_f32_16x16x32_bf16 v[80:83], v[184:187], v[208:211], v[80:83]
	v_mfma_f32_16x16x32_bf16 v[68:71], v[144:147], v[212:215], v[68:71]
	v_mfma_f32_16x16x32_bf16 v[68:71], v[148:151], v[216:219], v[68:71]
	v_mfma_f32_16x16x32_bf16 v[64:67], v[180:183], v[212:215], v[64:67]
	v_mfma_f32_16x16x32_bf16 v[64:67], v[184:187], v[216:219], v[64:67]
	s_setprio 0
	s_barrier
	s_add_i32 s41, s68, s33
	v_lshl_add_u64 v[172:173], s[30:31], 0, v[154:155]
	s_mov_b32 m0, s41
	v_lshl_add_u64 v[220:221], s[30:31], 0, v[158:159]
	global_load_lds_dwordx4 v[172:173], off
	s_add_i32 m0, s41, 0x2000
	s_add_u32 s42, s30, 0x100000
	s_addc_u32 s43, s31, 0
	s_add_i32 s41, s69, s33
	global_load_lds_dwordx4 v[220:221], off
	v_lshl_add_u64 v[188:189], s[42:43], 0, v[154:155]
	s_mov_b32 m0, s41
	v_lshl_add_u64 v[222:223], s[34:35], 0, v[152:153]
	global_load_lds_dwordx4 v[188:189], off
	v_lshl_add_u64 v[188:189], s[42:43], 0, v[158:159]
	s_add_i32 m0, s41, 0x2000
	v_lshl_add_u64 v[224:225], s[34:35], 0, v[156:157]
	global_load_lds_dwordx4 v[188:189], off
	s_mov_b32 m0, s7
	s_nop 0
	global_load_lds_dwordx4 v[222:223], off
	s_mov_b32 m0, s59
	s_nop 0
	global_load_lds_dwordx4 v[224:225], off
	ds_read_b128 v[188:191], v178 offset:16384
	ds_read_b128 v[192:195], v178 offset:17408
	ds_read_b128 v[196:199], v178 offset:18432
	ds_read_b128 v[200:203], v178 offset:19456
	ds_read_b128 v[204:207], v178 offset:20480
	ds_read_b128 v[208:211], v178 offset:21504
	ds_read_b128 v[212:215], v178 offset:22528
	ds_read_b128 v[216:219], v178 offset:23552
	s_waitcnt vmcnt(8)
	s_waitcnt lgkmcnt(0)
	s_barrier
	s_setprio 1
	s_waitcnt lgkmcnt(0)
	v_mfma_f32_16x16x32_bf16 v[60:63], v[128:131], v[188:191], v[60:63]
	v_mfma_f32_16x16x32_bf16 v[60:63], v[132:135], v[192:195], v[60:63]
	v_mfma_f32_16x16x32_bf16 v[56:59], v[136:139], v[188:191], v[56:59]
	v_mfma_f32_16x16x32_bf16 v[56:59], v[140:143], v[192:195], v[56:59]
	v_mfma_f32_16x16x32_bf16 v[44:47], v[128:131], v[196:199], v[44:47]
	v_mfma_f32_16x16x32_bf16 v[44:47], v[132:135], v[200:203], v[44:47]
	v_mfma_f32_16x16x32_bf16 v[40:43], v[136:139], v[196:199], v[40:43]
	v_mfma_f32_16x16x32_bf16 v[40:43], v[140:143], v[200:203], v[40:43]
	v_mfma_f32_16x16x32_bf16 v[28:31], v[128:131], v[204:207], v[28:31]
	v_mfma_f32_16x16x32_bf16 v[28:31], v[132:135], v[208:211], v[28:31]
	v_mfma_f32_16x16x32_bf16 v[24:27], v[136:139], v[204:207], v[24:27]
	v_mfma_f32_16x16x32_bf16 v[24:27], v[140:143], v[208:211], v[24:27]
	v_mfma_f32_16x16x32_bf16 v[12:15], v[128:131], v[212:215], v[12:15]
	v_mfma_f32_16x16x32_bf16 v[12:15], v[132:135], v[216:219], v[12:15]
	v_mfma_f32_16x16x32_bf16 v[8:11], v[136:139], v[212:215], v[8:11]
	v_mfma_f32_16x16x32_bf16 v[8:11], v[140:143], v[216:219], v[8:11]
	s_setprio 0
	s_setprio 1
	v_mfma_f32_16x16x32_bf16 v[52:55], v[144:147], v[188:191], v[52:55]
	v_mfma_f32_16x16x32_bf16 v[52:55], v[148:151], v[192:195], v[52:55]
	v_mfma_f32_16x16x32_bf16 v[48:51], v[180:183], v[188:191], v[48:51]
	v_mfma_f32_16x16x32_bf16 v[48:51], v[184:187], v[192:195], v[48:51]
	v_mfma_f32_16x16x32_bf16 v[36:39], v[144:147], v[196:199], v[36:39]
	v_mfma_f32_16x16x32_bf16 v[36:39], v[148:151], v[200:203], v[36:39]
	v_mfma_f32_16x16x32_bf16 v[32:35], v[180:183], v[196:199], v[32:35]
	v_mfma_f32_16x16x32_bf16 v[32:35], v[184:187], v[200:203], v[32:35]
	v_mfma_f32_16x16x32_bf16 v[20:23], v[144:147], v[204:207], v[20:23]
	v_mfma_f32_16x16x32_bf16 v[20:23], v[148:151], v[208:211], v[20:23]
	v_mfma_f32_16x16x32_bf16 v[16:19], v[180:183], v[204:207], v[16:19]
	v_mfma_f32_16x16x32_bf16 v[16:19], v[184:187], v[208:211], v[16:19]
	v_mfma_f32_16x16x32_bf16 v[4:7], v[144:147], v[212:215], v[4:7]
	v_mfma_f32_16x16x32_bf16 v[4:7], v[148:151], v[216:219], v[4:7]
	v_mfma_f32_16x16x32_bf16 v[0:3], v[180:183], v[212:215], v[0:3]
	v_mfma_f32_16x16x32_bf16 v[0:3], v[184:187], v[216:219], v[0:3]
	s_setprio 0
	s_barrier
	s_add_i32 s41, 0, 0x18000
	s_add_i32 s42, 0, 0x1c000
	v_add_u32_e32 v140, s41, v174
	v_add_u32_e32 v184, s42, v174
	ds_read_b128 v[128:131], v140
	ds_read_b128 v[132:135], v140 offset:1024
	ds_read_b128 v[136:139], v140 offset:2048
	ds_read_b128 v[140:143], v140 offset:3072
	ds_read_b128 v[144:147], v184
	ds_read_b128 v[148:151], v184 offset:1024
	ds_read_b128 v[180:183], v184 offset:2048
	ds_read_b128 v[184:187], v184 offset:3072
	s_add_u32 s34, s34, 0x100000
	s_addc_u32 s35, s35, 0
	s_mov_b32 m0, s60
	v_lshl_add_u64 v[188:189], s[34:35], 0, v[152:153]
	global_load_lds_dwordx4 v[188:189], off
	v_lshl_add_u64 v[188:189], s[34:35], 0, v[156:157]
	s_mov_b32 m0, s61
	s_nop 0
	global_load_lds_dwordx4 v[188:189], off
	ds_read_b128 v[188:191], v178 offset:32768
	ds_read_b128 v[192:195], v178 offset:33792
	ds_read_b128 v[196:199], v178 offset:34816
	ds_read_b128 v[200:203], v178 offset:35840
	ds_read_b128 v[204:207], v178 offset:36864
	ds_read_b128 v[208:211], v178 offset:37888
	ds_read_b128 v[212:215], v178 offset:38912
	ds_read_b128 v[216:219], v178 offset:39936
	s_waitcnt vmcnt(8)
	s_waitcnt lgkmcnt(0)
	s_barrier
	s_setprio 1
	s_waitcnt lgkmcnt(0)
	v_mfma_f32_16x16x32_bf16 v[124:127], v[128:131], v[188:191], v[124:127]
	v_mfma_f32_16x16x32_bf16 v[124:127], v[132:135], v[192:195], v[124:127]
	v_mfma_f32_16x16x32_bf16 v[120:123], v[136:139], v[188:191], v[120:123]
	v_mfma_f32_16x16x32_bf16 v[120:123], v[140:143], v[192:195], v[120:123]
	v_mfma_f32_16x16x32_bf16 v[108:111], v[128:131], v[196:199], v[108:111]
	v_mfma_f32_16x16x32_bf16 v[108:111], v[132:135], v[200:203], v[108:111]
	v_mfma_f32_16x16x32_bf16 v[104:107], v[136:139], v[196:199], v[104:107]
	v_mfma_f32_16x16x32_bf16 v[104:107], v[140:143], v[200:203], v[104:107]
	v_mfma_f32_16x16x32_bf16 v[92:95], v[128:131], v[204:207], v[92:95]
	v_mfma_f32_16x16x32_bf16 v[92:95], v[132:135], v[208:211], v[92:95]
	v_mfma_f32_16x16x32_bf16 v[88:91], v[136:139], v[204:207], v[88:91]
	v_mfma_f32_16x16x32_bf16 v[88:91], v[140:143], v[208:211], v[88:91]
	v_mfma_f32_16x16x32_bf16 v[76:79], v[128:131], v[212:215], v[76:79]
	v_mfma_f32_16x16x32_bf16 v[76:79], v[132:135], v[216:219], v[76:79]
	v_mfma_f32_16x16x32_bf16 v[72:75], v[136:139], v[212:215], v[72:75]
	v_mfma_f32_16x16x32_bf16 v[72:75], v[140:143], v[216:219], v[72:75]
	s_setprio 0
	s_setprio 1
	v_mfma_f32_16x16x32_bf16 v[116:119], v[144:147], v[188:191], v[116:119]
	v_mfma_f32_16x16x32_bf16 v[116:119], v[148:151], v[192:195], v[116:119]
	v_mfma_f32_16x16x32_bf16 v[112:115], v[180:183], v[188:191], v[112:115]
	v_mfma_f32_16x16x32_bf16 v[112:115], v[184:187], v[192:195], v[112:115]
	v_mfma_f32_16x16x32_bf16 v[100:103], v[144:147], v[196:199], v[100:103]
	v_mfma_f32_16x16x32_bf16 v[100:103], v[148:151], v[200:203], v[100:103]
	v_mfma_f32_16x16x32_bf16 v[96:99], v[180:183], v[196:199], v[96:99]
	v_mfma_f32_16x16x32_bf16 v[96:99], v[184:187], v[200:203], v[96:99]
	v_mfma_f32_16x16x32_bf16 v[84:87], v[144:147], v[204:207], v[84:87]
	v_mfma_f32_16x16x32_bf16 v[84:87], v[148:151], v[208:211], v[84:87]
	v_mfma_f32_16x16x32_bf16 v[80:83], v[180:183], v[204:207], v[80:83]
	v_mfma_f32_16x16x32_bf16 v[80:83], v[184:187], v[208:211], v[80:83]
	v_mfma_f32_16x16x32_bf16 v[68:71], v[144:147], v[212:215], v[68:71]
	v_mfma_f32_16x16x32_bf16 v[68:71], v[148:151], v[216:219], v[68:71]
	v_mfma_f32_16x16x32_bf16 v[64:67], v[180:183], v[212:215], v[64:67]
	v_mfma_f32_16x16x32_bf16 v[64:67], v[184:187], v[216:219], v[64:67]
	s_setprio 0
	s_barrier
	s_add_i32 s34, s41, s33
	v_lshl_add_u64 v[172:173], v[172:173], 0, s[16:17]
	s_mov_b32 m0, s34
	s_nop 0
	global_load_lds_dwordx4 v[172:173], off
	s_add_i32 m0, s34, 0x2000
	s_add_u32 s30, s30, 0x100800
	v_lshl_add_u64 v[172:173], v[220:221], 0, s[16:17]
	s_addc_u32 s31, s31, 0
	s_add_i32 s34, s42, s33
	global_load_lds_dwordx4 v[172:173], off
	v_lshl_add_u64 v[172:173], s[30:31], 0, v[154:155]
	s_mov_b32 m0, s34
	s_nop 0
	global_load_lds_dwordx4 v[172:173], off
	v_lshl_add_u64 v[172:173], s[30:31], 0, v[158:159]
	s_add_i32 m0, s34, 0x2000
	s_nop 0
	global_load_lds_dwordx4 v[172:173], off
	v_lshl_add_u64 v[172:173], v[222:223], 0, s[18:19]
	s_mov_b32 m0, s63
	s_nop 0
	global_load_lds_dwordx4 v[172:173], off
	v_lshl_add_u64 v[172:173], v[224:225], 0, s[18:19]
	s_mov_b32 m0, s64
	s_nop 0
	global_load_lds_dwordx4 v[172:173], off
	ds_read_b128 v[188:191], v178 offset:49152
	ds_read_b128 v[192:195], v178 offset:50176
	ds_read_b128 v[196:199], v178 offset:51200
	ds_read_b128 v[200:203], v178 offset:52224
	ds_read_b128 v[204:207], v178 offset:53248
	ds_read_b128 v[208:211], v178 offset:54272
	ds_read_b128 v[212:215], v178 offset:55296
	ds_read_b128 v[216:219], v178 offset:56320
	s_waitcnt vmcnt(8)
	s_waitcnt lgkmcnt(0)
	s_barrier
	s_setprio 1
	s_waitcnt lgkmcnt(0)
	v_mfma_f32_16x16x32_bf16 v[60:63], v[128:131], v[188:191], v[60:63]
	v_mfma_f32_16x16x32_bf16 v[60:63], v[132:135], v[192:195], v[60:63]
	v_mfma_f32_16x16x32_bf16 v[56:59], v[136:139], v[188:191], v[56:59]
	v_mfma_f32_16x16x32_bf16 v[56:59], v[140:143], v[192:195], v[56:59]
	v_mfma_f32_16x16x32_bf16 v[44:47], v[128:131], v[196:199], v[44:47]
	v_mfma_f32_16x16x32_bf16 v[44:47], v[132:135], v[200:203], v[44:47]
	v_mfma_f32_16x16x32_bf16 v[40:43], v[136:139], v[196:199], v[40:43]
	v_mfma_f32_16x16x32_bf16 v[40:43], v[140:143], v[200:203], v[40:43]
	v_mfma_f32_16x16x32_bf16 v[28:31], v[128:131], v[204:207], v[28:31]
	v_mfma_f32_16x16x32_bf16 v[28:31], v[132:135], v[208:211], v[28:31]
	v_mfma_f32_16x16x32_bf16 v[24:27], v[136:139], v[204:207], v[24:27]
	v_mfma_f32_16x16x32_bf16 v[24:27], v[140:143], v[208:211], v[24:27]
	v_mfma_f32_16x16x32_bf16 v[12:15], v[128:131], v[212:215], v[12:15]
	v_mfma_f32_16x16x32_bf16 v[12:15], v[132:135], v[216:219], v[12:15]
	v_mfma_f32_16x16x32_bf16 v[8:11], v[136:139], v[212:215], v[8:11]
	v_mfma_f32_16x16x32_bf16 v[8:11], v[140:143], v[216:219], v[8:11]
	s_setprio 0
	s_setprio 1
	v_mfma_f32_16x16x32_bf16 v[52:55], v[144:147], v[188:191], v[52:55]
	v_mfma_f32_16x16x32_bf16 v[52:55], v[148:151], v[192:195], v[52:55]
	v_mfma_f32_16x16x32_bf16 v[48:51], v[180:183], v[188:191], v[48:51]
	v_mfma_f32_16x16x32_bf16 v[48:51], v[184:187], v[192:195], v[48:51]
	v_mfma_f32_16x16x32_bf16 v[36:39], v[144:147], v[196:199], v[36:39]
	v_mfma_f32_16x16x32_bf16 v[36:39], v[148:151], v[200:203], v[36:39]
	v_mfma_f32_16x16x32_bf16 v[32:35], v[180:183], v[196:199], v[32:35]
	v_mfma_f32_16x16x32_bf16 v[32:35], v[184:187], v[200:203], v[32:35]
	v_mfma_f32_16x16x32_bf16 v[20:23], v[144:147], v[204:207], v[20:23]
	v_mfma_f32_16x16x32_bf16 v[20:23], v[148:151], v[208:211], v[20:23]
	v_mfma_f32_16x16x32_bf16 v[16:19], v[180:183], v[204:207], v[16:19]
	v_mfma_f32_16x16x32_bf16 v[16:19], v[184:187], v[208:211], v[16:19]
	v_mfma_f32_16x16x32_bf16 v[4:7], v[144:147], v[212:215], v[4:7]
	v_mfma_f32_16x16x32_bf16 v[4:7], v[148:151], v[216:219], v[4:7]
	v_mfma_f32_16x16x32_bf16 v[0:3], v[180:183], v[212:215], v[0:3]
	v_mfma_f32_16x16x32_bf16 v[0:3], v[184:187], v[216:219], v[0:3]
	s_setprio 0
	s_barrier
	s_add_i32 s40, s40, 2
	s_add_u32 s38, s38, 0x1000
	s_addc_u32 s39, s39, 0
	s_add_u32 s28, s28, 0x100
	s_addc_u32 s29, s29, 0
	s_cmp_gt_u32 s40, 61
	s_cbranch_scc0 .LBB0_1202
	s_and_b64 vcc, exec, s[10:11]
	s_cbranch_vccz .LBB0_1205
	s_barrier

.LBB0_1263:
	ds_read_b128 v[146:149], v152
	ds_read_b128 v[156:159], v152 offset:1024
	ds_read_b128 v[160:163], v152 offset:2048
	ds_read_b128 v[164:167], v152 offset:3072
	ds_read_b128 v[168:171], v153
	ds_read_b128 v[172:175], v153 offset:1024
	ds_read_b128 v[176:179], v153 offset:2048
	ds_read_b128 v[180:183], v153 offset:3072
	s_add_u32 s22, s20, 0x100
	s_addc_u32 s23, s21, 0
	s_cmp_eq_u32 s46, 12
	s_cselect_b32 s27, s5, s23
	s_cselect_b32 s26, s4, s22
	s_cselect_b32 s25, s19, s15
	s_cselect_b32 s24, s18, s6
	v_lshl_add_u64 v[184:185], s[20:21], 0, v[136:137]
	s_add_i32 m0, s17, 0xc000
	s_nop 0
	global_load_lds_dwordx4 v[184:185], off
	v_lshl_add_u64 v[184:185], s[20:21], 0, v[138:139]
	s_add_i32 m0, s17, 0xe000
	s_nop 0
	global_load_lds_dwordx4 v[184:185], off
	ds_read_b128 v[184:187], v154
	ds_read_b128 v[188:191], v154 offset:1024
	ds_read_b128 v[192:195], v154 offset:2048
	ds_read_b128 v[196:199], v154 offset:3072
	ds_read_b128 v[200:203], v154 offset:4096
	ds_read_b128 v[204:207], v154 offset:5120
	ds_read_b128 v[208:211], v154 offset:6144
	ds_read_b128 v[212:215], v154 offset:7168
	s_waitcnt vmcnt(8)
	s_waitcnt lgkmcnt(0)
	s_barrier
	s_setprio 1
	s_waitcnt lgkmcnt(0)
	v_mfma_f32_16x16x32_bf16 v[124:127], v[146:149], v[184:187], v[124:127]
	v_mfma_f32_16x16x32_bf16 v[124:127], v[156:159], v[188:191], v[124:127]
	v_mfma_f32_16x16x32_bf16 v[120:123], v[160:163], v[184:187], v[120:123]
	v_mfma_f32_16x16x32_bf16 v[120:123], v[164:167], v[188:191], v[120:123]
	v_mfma_f32_16x16x32_bf16 v[112:115], v[146:149], v[192:195], v[112:115]
	v_mfma_f32_16x16x32_bf16 v[112:115], v[156:159], v[196:199], v[112:115]
	v_mfma_f32_16x16x32_bf16 v[104:107], v[160:163], v[192:195], v[104:107]
	v_mfma_f32_16x16x32_bf16 v[104:107], v[164:167], v[196:199], v[104:107]
	v_mfma_f32_16x16x32_bf16 v[96:99], v[146:149], v[200:203], v[96:99]
	v_mfma_f32_16x16x32_bf16 v[96:99], v[156:159], v[204:207], v[96:99]
	v_mfma_f32_16x16x32_bf16 v[88:91], v[160:163], v[200:203], v[88:91]
	v_mfma_f32_16x16x32_bf16 v[88:91], v[164:167], v[204:207], v[88:91]
	v_mfma_f32_16x16x32_bf16 v[80:83], v[146:149], v[208:211], v[80:83]
	v_mfma_f32_16x16x32_bf16 v[80:83], v[156:159], v[212:215], v[80:83]
	v_mfma_f32_16x16x32_bf16 v[72:75], v[160:163], v[208:211], v[72:75]
	v_mfma_f32_16x16x32_bf16 v[72:75], v[164:167], v[212:215], v[72:75]
	s_setprio 0
	s_setprio 1
	v_mfma_f32_16x16x32_bf16 v[116:119], v[168:171], v[184:187], v[116:119]
	v_mfma_f32_16x16x32_bf16 v[116:119], v[172:175], v[188:191], v[116:119]
	v_mfma_f32_16x16x32_bf16 v[108:111], v[176:179], v[184:187], v[108:111]
	v_mfma_f32_16x16x32_bf16 v[108:111], v[180:183], v[188:191], v[108:111]
	v_mfma_f32_16x16x32_bf16 v[100:103], v[168:171], v[192:195], v[100:103]
	v_mfma_f32_16x16x32_bf16 v[100:103], v[172:175], v[196:199], v[100:103]
	v_mfma_f32_16x16x32_bf16 v[92:95], v[176:179], v[192:195], v[92:95]
	v_mfma_f32_16x16x32_bf16 v[92:95], v[180:183], v[196:199], v[92:95]
	v_mfma_f32_16x16x32_bf16 v[84:87], v[168:171], v[200:203], v[84:87]
	v_mfma_f32_16x16x32_bf16 v[84:87], v[172:175], v[204:207], v[84:87]
	v_mfma_f32_16x16x32_bf16 v[76:79], v[176:179], v[200:203], v[76:79]
	v_mfma_f32_16x16x32_bf16 v[76:79], v[180:183], v[204:207], v[76:79]
	v_mfma_f32_16x16x32_bf16 v[68:71], v[168:171], v[208:211], v[68:71]
	v_mfma_f32_16x16x32_bf16 v[68:71], v[172:175], v[212:215], v[68:71]
	v_mfma_f32_16x16x32_bf16 v[64:67], v[176:179], v[208:211], v[64:67]
	v_mfma_f32_16x16x32_bf16 v[64:67], v[180:183], v[212:215], v[64:67]
	s_setprio 0
	s_barrier
	s_add_i32 s20, s41, s33
	v_lshl_add_u64 v[216:217], s[24:25], 0, v[130:131]
	s_mov_b32 m0, s20
	v_lshl_add_u64 v[218:219], s[24:25], 0, v[134:135]
	global_load_lds_dwordx4 v[216:217], off
	s_add_i32 m0, s20, 0x2000
	s_add_u32 s20, s24, 0x200000
	s_addc_u32 s21, s25, 0
	s_add_i32 s47, s42, s33
	global_load_lds_dwordx4 v[218:219], off
	v_lshl_add_u64 v[184:185], s[20:21], 0, v[130:131]
	s_mov_b32 m0, s47
	v_lshl_add_u64 v[220:221], s[26:27], 0, v[128:129]
	global_load_lds_dwordx4 v[184:185], off
	v_lshl_add_u64 v[184:185], s[20:21], 0, v[134:135]
	s_add_i32 m0, s47, 0x2000
	v_lshl_add_u64 v[222:223], s[26:27], 0, v[132:133]
	global_load_lds_dwordx4 v[184:185], off
	s_mov_b32 m0, s17
	s_nop 0
	global_load_lds_dwordx4 v[220:221], off
	s_mov_b32 m0, s34
	s_nop 0
	global_load_lds_dwordx4 v[222:223], off
	ds_read_b128 v[184:187], v154 offset:16384
	ds_read_b128 v[188:191], v154 offset:17408
	ds_read_b128 v[192:195], v154 offset:18432
	ds_read_b128 v[196:199], v154 offset:19456
	ds_read_b128 v[200:203], v154 offset:20480
	ds_read_b128 v[204:207], v154 offset:21504
	ds_read_b128 v[208:211], v154 offset:22528
	ds_read_b128 v[212:215], v154 offset:23552
	s_waitcnt vmcnt(8)
	s_waitcnt lgkmcnt(0)
	s_barrier
	s_setprio 1
	s_waitcnt lgkmcnt(0)
	v_mfma_f32_16x16x32_bf16 v[60:63], v[146:149], v[184:187], v[60:63]
	v_mfma_f32_16x16x32_bf16 v[60:63], v[156:159], v[188:191], v[60:63]
	v_mfma_f32_16x16x32_bf16 v[56:59], v[160:163], v[184:187], v[56:59]
	v_mfma_f32_16x16x32_bf16 v[56:59], v[164:167], v[188:191], v[56:59]
	v_mfma_f32_16x16x32_bf16 v[48:51], v[146:149], v[192:195], v[48:51]
	v_mfma_f32_16x16x32_bf16 v[48:51], v[156:159], v[196:199], v[48:51]
	v_mfma_f32_16x16x32_bf16 v[40:43], v[160:163], v[192:195], v[40:43]
	v_mfma_f32_16x16x32_bf16 v[40:43], v[164:167], v[196:199], v[40:43]
	v_mfma_f32_16x16x32_bf16 v[32:35], v[146:149], v[200:203], v[32:35]
	v_mfma_f32_16x16x32_bf16 v[32:35], v[156:159], v[204:207], v[32:35]
	v_mfma_f32_16x16x32_bf16 v[24:27], v[160:163], v[200:203], v[24:27]
	v_mfma_f32_16x16x32_bf16 v[24:27], v[164:167], v[204:207], v[24:27]
	v_mfma_f32_16x16x32_bf16 v[16:19], v[146:149], v[208:211], v[16:19]
	v_mfma_f32_16x16x32_bf16 v[16:19], v[156:159], v[212:215], v[16:19]
	v_mfma_f32_16x16x32_bf16 v[8:11], v[160:163], v[208:211], v[8:11]
	v_mfma_f32_16x16x32_bf16 v[8:11], v[164:167], v[212:215], v[8:11]
	s_setprio 0
	s_setprio 1
	v_mfma_f32_16x16x32_bf16 v[52:55], v[168:171], v[184:187], v[52:55]
	v_mfma_f32_16x16x32_bf16 v[52:55], v[172:175], v[188:191], v[52:55]
	v_mfma_f32_16x16x32_bf16 v[44:47], v[176:179], v[184:187], v[44:47]
	v_mfma_f32_16x16x32_bf16 v[44:47], v[180:183], v[188:191], v[44:47]
	v_mfma_f32_16x16x32_bf16 v[36:39], v[168:171], v[192:195], v[36:39]
	v_mfma_f32_16x16x32_bf16 v[36:39], v[172:175], v[196:199], v[36:39]
	v_mfma_f32_16x16x32_bf16 v[28:31], v[176:179], v[192:195], v[28:31]
	v_mfma_f32_16x16x32_bf16 v[28:31], v[180:183], v[196:199], v[28:31]
	v_mfma_f32_16x16x32_bf16 v[20:23], v[168:171], v[200:203], v[20:23]
	v_mfma_f32_16x16x32_bf16 v[20:23], v[172:175], v[204:207], v[20:23]
	v_mfma_f32_16x16x32_bf16 v[12:15], v[176:179], v[200:203], v[12:15]
	v_mfma_f32_16x16x32_bf16 v[12:15], v[180:183], v[204:207], v[12:15]
	v_mfma_f32_16x16x32_bf16 v[4:7], v[168:171], v[208:211], v[4:7]
	v_mfma_f32_16x16x32_bf16 v[4:7], v[172:175], v[212:215], v[4:7]
	v_mfma_f32_16x16x32_bf16 v[0:3], v[176:179], v[208:211], v[0:3]
	v_mfma_f32_16x16x32_bf16 v[0:3], v[180:183], v[212:215], v[0:3]
	s_setprio 0
	s_barrier
	s_add_i32 s47, 0, 0x18000
	v_add_u32_e32 v144, s47, v145
	s_add_i32 s48, 0, 0x1c000
	ds_read_b128 v[146:149], v144
	ds_read_b128 v[156:159], v144 offset:1024
	ds_read_b128 v[160:163], v144 offset:2048
	ds_read_b128 v[164:167], v144 offset:3072
	v_add_u32_e32 v144, s48, v145
	ds_read_b128 v[168:171], v144
	ds_read_b128 v[172:175], v144 offset:1024
	ds_read_b128 v[176:179], v144 offset:2048
	ds_read_b128 v[180:183], v144 offset:3072
	s_add_u32 s20, s26, 0x200000
	s_addc_u32 s21, s27, 0
	s_mov_b32 m0, s35
	v_lshl_add_u64 v[184:185], s[20:21], 0, v[128:129]
	global_load_lds_dwordx4 v[184:185], off
	v_lshl_add_u64 v[184:185], s[20:21], 0, v[132:133]
	s_mov_b32 m0, s36
	s_nop 0
	global_load_lds_dwordx4 v[184:185], off
	ds_read_b128 v[184:187], v154 offset:32768
	ds_read_b128 v[188:191], v154 offset:33792
	ds_read_b128 v[192:195], v154 offset:34816
	ds_read_b128 v[196:199], v154 offset:35840
	ds_read_b128 v[200:203], v154 offset:36864
	ds_read_b128 v[204:207], v154 offset:37888
	ds_read_b128 v[208:211], v154 offset:38912
	ds_read_b128 v[212:215], v154 offset:39936
	s_waitcnt vmcnt(8)
	s_waitcnt lgkmcnt(0)
	s_barrier
	s_setprio 1
	s_waitcnt lgkmcnt(0)
	v_mfma_f32_16x16x32_bf16 v[124:127], v[146:149], v[184:187], v[124:127]
	v_mfma_f32_16x16x32_bf16 v[124:127], v[156:159], v[188:191], v[124:127]
	v_mfma_f32_16x16x32_bf16 v[120:123], v[160:163], v[184:187], v[120:123]
	v_mfma_f32_16x16x32_bf16 v[120:123], v[164:167], v[188:191], v[120:123]
	v_mfma_f32_16x16x32_bf16 v[112:115], v[146:149], v[192:195], v[112:115]
	v_mfma_f32_16x16x32_bf16 v[112:115], v[156:159], v[196:199], v[112:115]
	v_mfma_f32_16x16x32_bf16 v[104:107], v[160:163], v[192:195], v[104:107]
	v_mfma_f32_16x16x32_bf16 v[104:107], v[164:167], v[196:199], v[104:107]
	v_mfma_f32_16x16x32_bf16 v[96:99], v[146:149], v[200:203], v[96:99]
	v_mfma_f32_16x16x32_bf16 v[96:99], v[156:159], v[204:207], v[96:99]
	v_mfma_f32_16x16x32_bf16 v[88:91], v[160:163], v[200:203], v[88:91]
	v_mfma_f32_16x16x32_bf16 v[88:91], v[164:167], v[204:207], v[88:91]
	v_mfma_f32_16x16x32_bf16 v[80:83], v[146:149], v[208:211], v[80:83]
	v_mfma_f32_16x16x32_bf16 v[80:83], v[156:159], v[212:215], v[80:83]
	v_mfma_f32_16x16x32_bf16 v[72:75], v[160:163], v[208:211], v[72:75]
	v_mfma_f32_16x16x32_bf16 v[72:75], v[164:167], v[212:215], v[72:75]
	s_setprio 0
	s_setprio 1
	v_mfma_f32_16x16x32_bf16 v[116:119], v[168:171], v[184:187], v[116:119]
	v_mfma_f32_16x16x32_bf16 v[116:119], v[172:175], v[188:191], v[116:119]
	v_mfma_f32_16x16x32_bf16 v[108:111], v[176:179], v[184:187], v[108:111]
	v_mfma_f32_16x16x32_bf16 v[108:111], v[180:183], v[188:191], v[108:111]
	v_mfma_f32_16x16x32_bf16 v[100:103], v[168:171], v[192:195], v[100:103]
	v_mfma_f32_16x16x32_bf16 v[100:103], v[172:175], v[196:199], v[100:103]
	v_mfma_f32_16x16x32_bf16 v[92:95], v[176:179], v[192:195], v[92:95]
	v_mfma_f32_16x16x32_bf16 v[92:95], v[180:183], v[196:199], v[92:95]
	v_mfma_f32_16x16x32_bf16 v[84:87], v[168:171], v[200:203], v[84:87]
	v_mfma_f32_16x16x32_bf16 v[84:87], v[172:175], v[204:207], v[84:87]
	v_mfma_f32_16x16x32_bf16 v[76:79], v[176:179], v[200:203], v[76:79]
	v_mfma_f32_16x16x32_bf16 v[76:79], v[180:183], v[204:207], v[76:79]
	v_mfma_f32_16x16x32_bf16 v[68:71], v[168:171], v[208:211], v[68:71]
	v_mfma_f32_16x16x32_bf16 v[68:71], v[172:175], v[212:215], v[68:71]
	v_mfma_f32_16x16x32_bf16 v[64:67], v[176:179], v[208:211], v[64:67]
	v_mfma_f32_16x16x32_bf16 v[64:67], v[180:183], v[212:215], v[64:67]
	s_setprio 0
	s_barrier
	s_add_i32 s20, s47, s33
	v_lshl_add_u64 v[184:185], v[216:217], 0, s[12:13]
	s_mov_b32 m0, s20
	s_nop 0
	global_load_lds_dwordx4 v[184:185], off
	s_add_i32 m0, s20, 0x2000
	s_add_u32 s20, s24, 0x200080
	v_lshl_add_u64 v[184:185], v[218:219], 0, s[12:13]
	s_addc_u32 s21, s25, 0
	s_add_i32 s24, s48, s33
	global_load_lds_dwordx4 v[184:185], off
	v_lshl_add_u64 v[184:185], s[20:21], 0, v[130:131]
	s_mov_b32 m0, s24
	s_nop 0
	global_load_lds_dwordx4 v[184:185], off
	v_lshl_add_u64 v[184:185], s[20:21], 0, v[134:135]
	s_add_i32 m0, s24, 0x2000
	s_nop 0
	global_load_lds_dwordx4 v[184:185], off
	v_lshl_add_u64 v[184:185], v[220:221], 0, s[12:13]
	s_mov_b32 m0, s37
	s_nop 0
	global_load_lds_dwordx4 v[184:185], off
	v_lshl_add_u64 v[184:185], v[222:223], 0, s[12:13]
	s_mov_b32 m0, s38
	s_nop 0
	global_load_lds_dwordx4 v[184:185], off
	ds_read_b128 v[184:187], v154 offset:49152
	ds_read_b128 v[188:191], v154 offset:50176
	ds_read_b128 v[192:195], v154 offset:51200
	ds_read_b128 v[196:199], v154 offset:52224
	ds_read_b128 v[200:203], v154 offset:53248
	ds_read_b128 v[204:207], v154 offset:54272
	ds_read_b128 v[208:211], v154 offset:55296
	ds_read_b128 v[212:215], v154 offset:56320
	s_waitcnt vmcnt(8)
	s_waitcnt lgkmcnt(0)
	s_barrier
	s_setprio 1
	s_waitcnt lgkmcnt(0)
	v_mfma_f32_16x16x32_bf16 v[60:63], v[146:149], v[184:187], v[60:63]
	v_mfma_f32_16x16x32_bf16 v[60:63], v[156:159], v[188:191], v[60:63]
	v_mfma_f32_16x16x32_bf16 v[56:59], v[160:163], v[184:187], v[56:59]
	v_mfma_f32_16x16x32_bf16 v[56:59], v[164:167], v[188:191], v[56:59]
	v_mfma_f32_16x16x32_bf16 v[48:51], v[146:149], v[192:195], v[48:51]
	v_mfma_f32_16x16x32_bf16 v[48:51], v[156:159], v[196:199], v[48:51]
	v_mfma_f32_16x16x32_bf16 v[40:43], v[160:163], v[192:195], v[40:43]
	v_mfma_f32_16x16x32_bf16 v[40:43], v[164:167], v[196:199], v[40:43]
	v_mfma_f32_16x16x32_bf16 v[32:35], v[146:149], v[200:203], v[32:35]
	v_mfma_f32_16x16x32_bf16 v[32:35], v[156:159], v[204:207], v[32:35]
	v_mfma_f32_16x16x32_bf16 v[24:27], v[160:163], v[200:203], v[24:27]
	v_mfma_f32_16x16x32_bf16 v[24:27], v[164:167], v[204:207], v[24:27]
	v_mfma_f32_16x16x32_bf16 v[16:19], v[146:149], v[208:211], v[16:19]
	v_mfma_f32_16x16x32_bf16 v[16:19], v[156:159], v[212:215], v[16:19]
	v_mfma_f32_16x16x32_bf16 v[8:11], v[160:163], v[208:211], v[8:11]
	v_mfma_f32_16x16x32_bf16 v[8:11], v[164:167], v[212:215], v[8:11]
	s_setprio 0
	s_setprio 1
	v_mfma_f32_16x16x32_bf16 v[52:55], v[168:171], v[184:187], v[52:55]
	v_mfma_f32_16x16x32_bf16 v[52:55], v[172:175], v[188:191], v[52:55]
	v_mfma_f32_16x16x32_bf16 v[44:47], v[176:179], v[184:187], v[44:47]
	v_mfma_f32_16x16x32_bf16 v[44:47], v[180:183], v[188:191], v[44:47]
	v_mfma_f32_16x16x32_bf16 v[36:39], v[168:171], v[192:195], v[36:39]
	v_mfma_f32_16x16x32_bf16 v[36:39], v[172:175], v[196:199], v[36:39]
	v_mfma_f32_16x16x32_bf16 v[28:31], v[176:179], v[192:195], v[28:31]
	v_mfma_f32_16x16x32_bf16 v[28:31], v[180:183], v[196:199], v[28:31]
	v_mfma_f32_16x16x32_bf16 v[20:23], v[168:171], v[200:203], v[20:23]
	v_mfma_f32_16x16x32_bf16 v[20:23], v[172:175], v[204:207], v[20:23]
	v_mfma_f32_16x16x32_bf16 v[12:15], v[176:179], v[200:203], v[12:15]
	v_mfma_f32_16x16x32_bf16 v[12:15], v[180:183], v[204:207], v[12:15]
	v_mfma_f32_16x16x32_bf16 v[4:7], v[168:171], v[208:211], v[4:7]
	v_mfma_f32_16x16x32_bf16 v[4:7], v[172:175], v[212:215], v[4:7]
	v_mfma_f32_16x16x32_bf16 v[0:3], v[176:179], v[208:211], v[0:3]
	v_mfma_f32_16x16x32_bf16 v[0:3], v[180:183], v[212:215], v[0:3]
	s_setprio 0
	s_barrier
	s_add_i32 s46, s46, 2
	s_add_u32 s6, s6, 0x100
	s_addc_u32 s15, s15, 0
	s_cmp_gt_u32 s46, 13
	s_mov_b64 s[20:21], s[22:23]
	s_cbranch_scc0 .LBB0_1263
	s_and_b64 vcc, exec, s[8:9]
	s_cbranch_vccz .LBB0_1266
	s_barrier

.LBB0_1340:
	v_add_u32_e32 v166, s51, v152
	v_add_u32_e32 v182, s52, v152
	ds_read_b128 v[154:157], v166
	ds_read_b128 v[158:161], v166 offset:1024
	ds_read_b128 v[162:165], v166 offset:2048
	ds_read_b128 v[166:169], v166 offset:3072
	ds_read_b128 v[170:173], v182
	ds_read_b128 v[174:177], v182 offset:1024
	ds_read_b128 v[178:181], v182 offset:2048
	ds_read_b128 v[182:185], v182 offset:3072
	s_add_u32 s30, s10, s28
	s_addc_u32 s31, s11, s29
	s_cmp_eq_u32 s58, 60
	s_cselect_b32 s35, s23, s31
	s_cselect_b32 s34, s54, s30
	s_cselect_b32 s31, s21, s57
	s_cselect_b32 s30, s55, s56
	v_lshl_add_u64 v[186:187], s[10:11], 0, v[146:147]
	s_add_i32 m0, s44, 0xc000
	s_nop 0
	global_load_lds_dwordx4 v[186:187], off
	v_lshl_add_u64 v[186:187], s[10:11], 0, v[144:145]
	s_add_i32 m0, s44, 0xe000
	s_nop 0
	global_load_lds_dwordx4 v[186:187], off
	ds_read_b128 v[186:189], v153
	ds_read_b128 v[190:193], v153 offset:1024
	ds_read_b128 v[194:197], v153 offset:2048
	ds_read_b128 v[198:201], v153 offset:3072
	ds_read_b128 v[202:205], v153 offset:4096
	ds_read_b128 v[206:209], v153 offset:5120
	ds_read_b128 v[210:213], v153 offset:6144
	ds_read_b128 v[214:217], v153 offset:7168
	s_waitcnt vmcnt(8)
	s_waitcnt lgkmcnt(0)
	s_barrier
	s_setprio 1
	s_waitcnt lgkmcnt(0)
	v_mfma_f32_16x16x32_bf16 v[124:127], v[154:157], v[186:189], v[124:127]
	v_mfma_f32_16x16x32_bf16 v[124:127], v[158:161], v[190:193], v[124:127]
	v_mfma_f32_16x16x32_bf16 v[120:123], v[162:165], v[186:189], v[120:123]
	v_mfma_f32_16x16x32_bf16 v[120:123], v[166:169], v[190:193], v[120:123]
	v_mfma_f32_16x16x32_bf16 v[108:111], v[154:157], v[194:197], v[108:111]
	v_mfma_f32_16x16x32_bf16 v[108:111], v[158:161], v[198:201], v[108:111]
	v_mfma_f32_16x16x32_bf16 v[104:107], v[162:165], v[194:197], v[104:107]
	v_mfma_f32_16x16x32_bf16 v[104:107], v[166:169], v[198:201], v[104:107]
	v_mfma_f32_16x16x32_bf16 v[92:95], v[154:157], v[202:205], v[92:95]
	v_mfma_f32_16x16x32_bf16 v[92:95], v[158:161], v[206:209], v[92:95]
	v_mfma_f32_16x16x32_bf16 v[88:91], v[162:165], v[202:205], v[88:91]
	v_mfma_f32_16x16x32_bf16 v[88:91], v[166:169], v[206:209], v[88:91]
	v_mfma_f32_16x16x32_bf16 v[76:79], v[154:157], v[210:213], v[76:79]
	v_mfma_f32_16x16x32_bf16 v[76:79], v[158:161], v[214:217], v[76:79]
	v_mfma_f32_16x16x32_bf16 v[72:75], v[162:165], v[210:213], v[72:75]
	v_mfma_f32_16x16x32_bf16 v[72:75], v[166:169], v[214:217], v[72:75]
	s_setprio 0
	s_setprio 1
	v_mfma_f32_16x16x32_bf16 v[116:119], v[170:173], v[186:189], v[116:119]
	v_mfma_f32_16x16x32_bf16 v[116:119], v[174:177], v[190:193], v[116:119]
	v_mfma_f32_16x16x32_bf16 v[112:115], v[178:181], v[186:189], v[112:115]
	v_mfma_f32_16x16x32_bf16 v[112:115], v[182:185], v[190:193], v[112:115]
	v_mfma_f32_16x16x32_bf16 v[100:103], v[170:173], v[194:197], v[100:103]
	v_mfma_f32_16x16x32_bf16 v[100:103], v[174:177], v[198:201], v[100:103]
	v_mfma_f32_16x16x32_bf16 v[96:99], v[178:181], v[194:197], v[96:99]
	v_mfma_f32_16x16x32_bf16 v[96:99], v[182:185], v[198:201], v[96:99]
	v_mfma_f32_16x16x32_bf16 v[84:87], v[170:173], v[202:205], v[84:87]
	v_mfma_f32_16x16x32_bf16 v[84:87], v[174:177], v[206:209], v[84:87]
	v_mfma_f32_16x16x32_bf16 v[80:83], v[178:181], v[202:205], v[80:83]
	v_mfma_f32_16x16x32_bf16 v[80:83], v[182:185], v[206:209], v[80:83]
	v_mfma_f32_16x16x32_bf16 v[68:71], v[170:173], v[210:213], v[68:71]
	v_mfma_f32_16x16x32_bf16 v[68:71], v[174:177], v[214:217], v[68:71]
	v_mfma_f32_16x16x32_bf16 v[64:67], v[178:181], v[210:213], v[64:67]
	v_mfma_f32_16x16x32_bf16 v[64:67], v[182:185], v[214:217], v[64:67]
	s_setprio 0
	s_barrier
	s_add_i32 s59, s51, s43
	v_lshl_add_u64 v[218:219], s[30:31], 0, v[130:131]
	s_mov_b32 m0, s59
	v_lshl_add_u64 v[220:221], s[30:31], 0, v[134:135]
	global_load_lds_dwordx4 v[218:219], off
	s_add_i32 m0, s59, 0x2000
	s_add_u32 s60, s30, 0x100000
	s_addc_u32 s61, s31, 0
	s_add_i32 s59, s52, s43
	global_load_lds_dwordx4 v[220:221], off
	v_lshl_add_u64 v[186:187], s[60:61], 0, v[130:131]
	s_mov_b32 m0, s59
	v_lshl_add_u64 v[222:223], s[34:35], 0, v[128:129]
	global_load_lds_dwordx4 v[186:187], off
	v_lshl_add_u64 v[186:187], s[60:61], 0, v[134:135]
	s_add_i32 m0, s59, 0x2000
	v_lshl_add_u64 v[224:225], s[34:35], 0, v[132:133]
	global_load_lds_dwordx4 v[186:187], off
	s_mov_b32 m0, s44
	s_nop 0
	global_load_lds_dwordx4 v[222:223], off
	s_mov_b32 m0, s45
	s_nop 0
	global_load_lds_dwordx4 v[224:225], off
	ds_read_b128 v[186:189], v153 offset:16384
	ds_read_b128 v[190:193], v153 offset:17408
	ds_read_b128 v[194:197], v153 offset:18432
	ds_read_b128 v[198:201], v153 offset:19456
	ds_read_b128 v[202:205], v153 offset:20480
	ds_read_b128 v[206:209], v153 offset:21504
	ds_read_b128 v[210:213], v153 offset:22528
	ds_read_b128 v[214:217], v153 offset:23552
	s_waitcnt vmcnt(8)
	s_waitcnt lgkmcnt(0)
	s_barrier
	s_setprio 1
	s_waitcnt lgkmcnt(0)
	v_mfma_f32_16x16x32_bf16 v[60:63], v[154:157], v[186:189], v[60:63]
	v_mfma_f32_16x16x32_bf16 v[60:63], v[158:161], v[190:193], v[60:63]
	v_mfma_f32_16x16x32_bf16 v[56:59], v[162:165], v[186:189], v[56:59]
	v_mfma_f32_16x16x32_bf16 v[56:59], v[166:169], v[190:193], v[56:59]
	v_mfma_f32_16x16x32_bf16 v[44:47], v[154:157], v[194:197], v[44:47]
	v_mfma_f32_16x16x32_bf16 v[44:47], v[158:161], v[198:201], v[44:47]
	v_mfma_f32_16x16x32_bf16 v[40:43], v[162:165], v[194:197], v[40:43]
	v_mfma_f32_16x16x32_bf16 v[40:43], v[166:169], v[198:201], v[40:43]
	v_mfma_f32_16x16x32_bf16 v[28:31], v[154:157], v[202:205], v[28:31]
	v_mfma_f32_16x16x32_bf16 v[28:31], v[158:161], v[206:209], v[28:31]
	v_mfma_f32_16x16x32_bf16 v[24:27], v[162:165], v[202:205], v[24:27]
	v_mfma_f32_16x16x32_bf16 v[24:27], v[166:169], v[206:209], v[24:27]
	v_mfma_f32_16x16x32_bf16 v[12:15], v[154:157], v[210:213], v[12:15]
	v_mfma_f32_16x16x32_bf16 v[12:15], v[158:161], v[214:217], v[12:15]
	v_mfma_f32_16x16x32_bf16 v[8:11], v[162:165], v[210:213], v[8:11]
	v_mfma_f32_16x16x32_bf16 v[8:11], v[166:169], v[214:217], v[8:11]
	s_setprio 0
	s_setprio 1
	v_mfma_f32_16x16x32_bf16 v[52:55], v[170:173], v[186:189], v[52:55]
	v_mfma_f32_16x16x32_bf16 v[52:55], v[174:177], v[190:193], v[52:55]
	v_mfma_f32_16x16x32_bf16 v[48:51], v[178:181], v[186:189], v[48:51]
	v_mfma_f32_16x16x32_bf16 v[48:51], v[182:185], v[190:193], v[48:51]
	v_mfma_f32_16x16x32_bf16 v[36:39], v[170:173], v[194:197], v[36:39]
	v_mfma_f32_16x16x32_bf16 v[36:39], v[174:177], v[198:201], v[36:39]
	v_mfma_f32_16x16x32_bf16 v[32:35], v[178:181], v[194:197], v[32:35]
	v_mfma_f32_16x16x32_bf16 v[32:35], v[182:185], v[198:201], v[32:35]
	v_mfma_f32_16x16x32_bf16 v[20:23], v[170:173], v[202:205], v[20:23]
	v_mfma_f32_16x16x32_bf16 v[20:23], v[174:177], v[206:209], v[20:23]
	v_mfma_f32_16x16x32_bf16 v[16:19], v[178:181], v[202:205], v[16:19]
	v_mfma_f32_16x16x32_bf16 v[16:19], v[182:185], v[206:209], v[16:19]
	v_mfma_f32_16x16x32_bf16 v[4:7], v[170:173], v[210:213], v[4:7]
	v_mfma_f32_16x16x32_bf16 v[4:7], v[174:177], v[214:217], v[4:7]
	v_mfma_f32_16x16x32_bf16 v[0:3], v[178:181], v[210:213], v[0:3]
	v_mfma_f32_16x16x32_bf16 v[0:3], v[182:185], v[214:217], v[0:3]
	s_setprio 0
	s_barrier
	s_add_i32 s59, 0, 0x18000
	s_add_i32 s60, 0, 0x1c000
	v_add_u32_e32 v166, s59, v152
	v_add_u32_e32 v182, s60, v152
	ds_read_b128 v[154:157], v166
	ds_read_b128 v[158:161], v166 offset:1024
	ds_read_b128 v[162:165], v166 offset:2048
	ds_read_b128 v[166:169], v166 offset:3072
	ds_read_b128 v[170:173], v182
	ds_read_b128 v[174:177], v182 offset:1024
	ds_read_b128 v[178:181], v182 offset:2048
	ds_read_b128 v[182:185], v182 offset:3072
	s_add_u32 s34, s34, 0x100000
	s_addc_u32 s35, s35, 0
	s_mov_b32 m0, s46
	v_lshl_add_u64 v[186:187], s[34:35], 0, v[128:129]
	global_load_lds_dwordx4 v[186:187], off
	v_lshl_add_u64 v[186:187], s[34:35], 0, v[132:133]
	s_mov_b32 m0, s47
	s_nop 0
	global_load_lds_dwordx4 v[186:187], off
	ds_read_b128 v[186:189], v153 offset:32768
	ds_read_b128 v[190:193], v153 offset:33792
	ds_read_b128 v[194:197], v153 offset:34816
	ds_read_b128 v[198:201], v153 offset:35840
	ds_read_b128 v[202:205], v153 offset:36864
	ds_read_b128 v[206:209], v153 offset:37888
	ds_read_b128 v[210:213], v153 offset:38912
	ds_read_b128 v[214:217], v153 offset:39936
	s_waitcnt vmcnt(8)
	s_waitcnt lgkmcnt(0)
	s_barrier
	s_setprio 1
	s_waitcnt lgkmcnt(0)
	v_mfma_f32_16x16x32_bf16 v[124:127], v[154:157], v[186:189], v[124:127]
	v_mfma_f32_16x16x32_bf16 v[124:127], v[158:161], v[190:193], v[124:127]
	v_mfma_f32_16x16x32_bf16 v[120:123], v[162:165], v[186:189], v[120:123]
	v_mfma_f32_16x16x32_bf16 v[120:123], v[166:169], v[190:193], v[120:123]
	v_mfma_f32_16x16x32_bf16 v[108:111], v[154:157], v[194:197], v[108:111]
	v_mfma_f32_16x16x32_bf16 v[108:111], v[158:161], v[198:201], v[108:111]
	v_mfma_f32_16x16x32_bf16 v[104:107], v[162:165], v[194:197], v[104:107]
	v_mfma_f32_16x16x32_bf16 v[104:107], v[166:169], v[198:201], v[104:107]
	v_mfma_f32_16x16x32_bf16 v[92:95], v[154:157], v[202:205], v[92:95]
	v_mfma_f32_16x16x32_bf16 v[92:95], v[158:161], v[206:209], v[92:95]
	v_mfma_f32_16x16x32_bf16 v[88:91], v[162:165], v[202:205], v[88:91]
	v_mfma_f32_16x16x32_bf16 v[88:91], v[166:169], v[206:209], v[88:91]
	v_mfma_f32_16x16x32_bf16 v[76:79], v[154:157], v[210:213], v[76:79]
	v_mfma_f32_16x16x32_bf16 v[76:79], v[158:161], v[214:217], v[76:79]
	v_mfma_f32_16x16x32_bf16 v[72:75], v[162:165], v[210:213], v[72:75]
	v_mfma_f32_16x16x32_bf16 v[72:75], v[166:169], v[214:217], v[72:75]
	s_setprio 0
	s_setprio 1
	v_mfma_f32_16x16x32_bf16 v[116:119], v[170:173], v[186:189], v[116:119]
	v_mfma_f32_16x16x32_bf16 v[116:119], v[174:177], v[190:193], v[116:119]
	v_mfma_f32_16x16x32_bf16 v[112:115], v[178:181], v[186:189], v[112:115]
	v_mfma_f32_16x16x32_bf16 v[112:115], v[182:185], v[190:193], v[112:115]
	v_mfma_f32_16x16x32_bf16 v[100:103], v[170:173], v[194:197], v[100:103]
	v_mfma_f32_16x16x32_bf16 v[100:103], v[174:177], v[198:201], v[100:103]
	v_mfma_f32_16x16x32_bf16 v[96:99], v[178:181], v[194:197], v[96:99]
	v_mfma_f32_16x16x32_bf16 v[96:99], v[182:185], v[198:201], v[96:99]
	v_mfma_f32_16x16x32_bf16 v[84:87], v[170:173], v[202:205], v[84:87]
	v_mfma_f32_16x16x32_bf16 v[84:87], v[174:177], v[206:209], v[84:87]
	v_mfma_f32_16x16x32_bf16 v[80:83], v[178:181], v[202:205], v[80:83]
	v_mfma_f32_16x16x32_bf16 v[80:83], v[182:185], v[206:209], v[80:83]
	v_mfma_f32_16x16x32_bf16 v[68:71], v[170:173], v[210:213], v[68:71]
	v_mfma_f32_16x16x32_bf16 v[68:71], v[174:177], v[214:217], v[68:71]
	v_mfma_f32_16x16x32_bf16 v[64:67], v[178:181], v[210:213], v[64:67]
	v_mfma_f32_16x16x32_bf16 v[64:67], v[182:185], v[214:217], v[64:67]
	s_setprio 0
	s_barrier
	s_add_i32 s34, s59, s43
	v_lshl_add_u64 v[186:187], v[218:219], 0, s[14:15]
	s_mov_b32 m0, s34
	s_nop 0
	global_load_lds_dwordx4 v[186:187], off
	s_add_i32 m0, s34, 0x2000
	s_add_u32 s30, s30, 0x100080
	v_lshl_add_u64 v[186:187], v[220:221], 0, s[14:15]
	s_addc_u32 s31, s31, 0
	s_add_i32 s34, s60, s43
	global_load_lds_dwordx4 v[186:187], off
	v_lshl_add_u64 v[186:187], s[30:31], 0, v[130:131]
	s_mov_b32 m0, s34
	s_nop 0
	global_load_lds_dwordx4 v[186:187], off
	v_lshl_add_u64 v[186:187], s[30:31], 0, v[134:135]
	s_add_i32 m0, s34, 0x2000
	s_nop 0
	global_load_lds_dwordx4 v[186:187], off
	v_lshl_add_u64 v[186:187], v[222:223], 0, s[16:17]
	s_mov_b32 m0, s49
	s_nop 0
	global_load_lds_dwordx4 v[186:187], off
	v_lshl_add_u64 v[186:187], v[224:225], 0, s[16:17]
	s_mov_b32 m0, s50
	s_nop 0
	global_load_lds_dwordx4 v[186:187], off
	ds_read_b128 v[186:189], v153 offset:49152
	ds_read_b128 v[190:193], v153 offset:50176
	ds_read_b128 v[194:197], v153 offset:51200
	ds_read_b128 v[198:201], v153 offset:52224
	ds_read_b128 v[202:205], v153 offset:53248
	ds_read_b128 v[206:209], v153 offset:54272
	ds_read_b128 v[210:213], v153 offset:55296
	ds_read_b128 v[214:217], v153 offset:56320
	s_waitcnt vmcnt(8)
	s_waitcnt lgkmcnt(0)
	s_barrier
	s_setprio 1
	s_waitcnt lgkmcnt(0)
	v_mfma_f32_16x16x32_bf16 v[60:63], v[154:157], v[186:189], v[60:63]
	v_mfma_f32_16x16x32_bf16 v[60:63], v[158:161], v[190:193], v[60:63]
	v_mfma_f32_16x16x32_bf16 v[56:59], v[162:165], v[186:189], v[56:59]
	v_mfma_f32_16x16x32_bf16 v[56:59], v[166:169], v[190:193], v[56:59]
	v_mfma_f32_16x16x32_bf16 v[44:47], v[154:157], v[194:197], v[44:47]
	v_mfma_f32_16x16x32_bf16 v[44:47], v[158:161], v[198:201], v[44:47]
	v_mfma_f32_16x16x32_bf16 v[40:43], v[162:165], v[194:197], v[40:43]
	v_mfma_f32_16x16x32_bf16 v[40:43], v[166:169], v[198:201], v[40:43]
	v_mfma_f32_16x16x32_bf16 v[28:31], v[154:157], v[202:205], v[28:31]
	v_mfma_f32_16x16x32_bf16 v[28:31], v[158:161], v[206:209], v[28:31]
	v_mfma_f32_16x16x32_bf16 v[24:27], v[162:165], v[202:205], v[24:27]
	v_mfma_f32_16x16x32_bf16 v[24:27], v[166:169], v[206:209], v[24:27]
	v_mfma_f32_16x16x32_bf16 v[12:15], v[154:157], v[210:213], v[12:15]
	v_mfma_f32_16x16x32_bf16 v[12:15], v[158:161], v[214:217], v[12:15]
	v_mfma_f32_16x16x32_bf16 v[8:11], v[162:165], v[210:213], v[8:11]
	v_mfma_f32_16x16x32_bf16 v[8:11], v[166:169], v[214:217], v[8:11]
	s_setprio 0
	s_setprio 1
	v_mfma_f32_16x16x32_bf16 v[52:55], v[170:173], v[186:189], v[52:55]
	v_mfma_f32_16x16x32_bf16 v[52:55], v[174:177], v[190:193], v[52:55]
	v_mfma_f32_16x16x32_bf16 v[48:51], v[178:181], v[186:189], v[48:51]
	v_mfma_f32_16x16x32_bf16 v[48:51], v[182:185], v[190:193], v[48:51]
	v_mfma_f32_16x16x32_bf16 v[36:39], v[170:173], v[194:197], v[36:39]
	v_mfma_f32_16x16x32_bf16 v[36:39], v[174:177], v[198:201], v[36:39]
	v_mfma_f32_16x16x32_bf16 v[32:35], v[178:181], v[194:197], v[32:35]
	v_mfma_f32_16x16x32_bf16 v[32:35], v[182:185], v[198:201], v[32:35]
	v_mfma_f32_16x16x32_bf16 v[20:23], v[170:173], v[202:205], v[20:23]
	v_mfma_f32_16x16x32_bf16 v[20:23], v[174:177], v[206:209], v[20:23]
	v_mfma_f32_16x16x32_bf16 v[16:19], v[178:181], v[202:205], v[16:19]
	v_mfma_f32_16x16x32_bf16 v[16:19], v[182:185], v[206:209], v[16:19]
	v_mfma_f32_16x16x32_bf16 v[4:7], v[170:173], v[210:213], v[4:7]
	v_mfma_f32_16x16x32_bf16 v[4:7], v[174:177], v[214:217], v[4:7]
	v_mfma_f32_16x16x32_bf16 v[0:3], v[178:181], v[210:213], v[0:3]
	v_mfma_f32_16x16x32_bf16 v[0:3], v[182:185], v[214:217], v[0:3]
	s_setprio 0
	s_barrier
	s_add_i32 s58, s58, 2
	s_add_u32 s56, s56, 0x100
	s_addc_u32 s57, s57, 0
	s_add_u32 s28, s28, 0x1000
	s_addc_u32 s29, s29, 0
	v_lshl_add_u64 v[146:147], v[146:147], 0, s[18:19]
	s_cmp_gt_u32 s58, 61
	v_lshl_add_u64 v[144:145], v[144:145], 0, s[18:19]
	s_cbranch_scc0 .LBB0_1340
	s_andn2_b64 vcc, exec, s[4:5]
	s_cbranch_vccnz .LBB0_1332
	v_mov_b32_e32 v0, 0
	s_mov_b32 s7, s20
	s_mov_b32 s6, s22
	s_mov_b64 s[8:9], s[26:27]
	s_mov_b64 s[10:11], s[24:25]
	s_mov_b32 s48, s53
	v_mov_b32_e32 v1, v0
	v_mov_b32_e32 v2, v0
	v_mov_b32_e32 v3, v0
	v_mov_b32_e32 v4, v0
	v_mov_b32_e32 v5, v0
	v_mov_b32_e32 v6, v0
	v_mov_b32_e32 v7, v0
	v_mov_b32_e32 v16, v0
	v_mov_b32_e32 v17, v0
	v_mov_b32_e32 v18, v0
	v_mov_b32_e32 v19, v0
	v_mov_b32_e32 v20, v0
	v_mov_b32_e32 v21, v0
	v_mov_b32_e32 v22, v0
	v_mov_b32_e32 v23, v0
	v_mov_b32_e32 v32, v0
	v_mov_b32_e32 v33, v0
	v_mov_b32_e32 v34, v0
	v_mov_b32_e32 v35, v0
	v_mov_b32_e32 v36, v0
	v_mov_b32_e32 v37, v0
	v_mov_b32_e32 v38, v0
	v_mov_b32_e32 v39, v0
	v_mov_b32_e32 v48, v0
	v_mov_b32_e32 v49, v0
	v_mov_b32_e32 v50, v0
	v_mov_b32_e32 v51, v0
	v_mov_b32_e32 v52, v0
	v_mov_b32_e32 v53, v0
	v_mov_b32_e32 v54, v0
	v_mov_b32_e32 v55, v0
	v_mov_b32_e32 v8, v0
	v_mov_b32_e32 v9, v0
	v_mov_b32_e32 v10, v0
	v_mov_b32_e32 v11, v0
	v_mov_b32_e32 v12, v0
	v_mov_b32_e32 v13, v0
	v_mov_b32_e32 v14, v0
	v_mov_b32_e32 v15, v0
	v_mov_b32_e32 v24, v0
	v_mov_b32_e32 v25, v0
	v_mov_b32_e32 v26, v0
	v_mov_b32_e32 v27, v0
	v_mov_b32_e32 v28, v0
	v_mov_b32_e32 v29, v0
	v_mov_b32_e32 v30, v0
	v_mov_b32_e32 v31, v0
	v_mov_b32_e32 v40, v0
	v_mov_b32_e32 v41, v0
	v_mov_b32_e32 v42, v0
	v_mov_b32_e32 v43, v0
	v_mov_b32_e32 v44, v0
	v_mov_b32_e32 v45, v0
	v_mov_b32_e32 v46, v0
	v_mov_b32_e32 v47, v0
	v_mov_b32_e32 v56, v0
	v_mov_b32_e32 v57, v0
	v_mov_b32_e32 v58, v0
	v_mov_b32_e32 v59, v0
	v_mov_b32_e32 v60, v0
	v_mov_b32_e32 v61, v0
	v_mov_b32_e32 v62, v0
	v_mov_b32_e32 v63, v0
	v_mov_b32_e32 v64, v0
	v_mov_b32_e32 v65, v0
	v_mov_b32_e32 v66, v0
	v_mov_b32_e32 v67, v0
	v_mov_b32_e32 v68, v0
	v_mov_b32_e32 v69, v0
	v_mov_b32_e32 v70, v0
	v_mov_b32_e32 v71, v0
	v_mov_b32_e32 v80, v0
	v_mov_b32_e32 v81, v0
	v_mov_b32_e32 v82, v0
	v_mov_b32_e32 v83, v0
	v_mov_b32_e32 v84, v0
	v_mov_b32_e32 v85, v0
	v_mov_b32_e32 v86, v0
	v_mov_b32_e32 v87, v0
	v_mov_b32_e32 v96, v0
	v_mov_b32_e32 v97, v0
	v_mov_b32_e32 v98, v0
	v_mov_b32_e32 v99, v0
	v_mov_b32_e32 v100, v0
	v_mov_b32_e32 v101, v0
	v_mov_b32_e32 v102, v0
	v_mov_b32_e32 v103, v0
	v_mov_b32_e32 v112, v0
	v_mov_b32_e32 v113, v0
	v_mov_b32_e32 v114, v0
	v_mov_b32_e32 v115, v0
	v_mov_b32_e32 v116, v0
	v_mov_b32_e32 v117, v0
	v_mov_b32_e32 v118, v0
	v_mov_b32_e32 v119, v0
	v_mov_b32_e32 v72, v0
	v_mov_b32_e32 v73, v0
	v_mov_b32_e32 v74, v0
	v_mov_b32_e32 v75, v0
	v_mov_b32_e32 v76, v0
	v_mov_b32_e32 v77, v0
	v_mov_b32_e32 v78, v0
	v_mov_b32_e32 v79, v0
	v_mov_b32_e32 v88, v0
	v_mov_b32_e32 v89, v0
	v_mov_b32_e32 v90, v0
	v_mov_b32_e32 v91, v0
	v_mov_b32_e32 v92, v0
	v_mov_b32_e32 v93, v0
	v_mov_b32_e32 v94, v0
	v_mov_b32_e32 v95, v0
	v_mov_b32_e32 v104, v0
	v_mov_b32_e32 v105, v0
	v_mov_b32_e32 v106, v0
	v_mov_b32_e32 v107, v0
	v_mov_b32_e32 v108, v0
	v_mov_b32_e32 v109, v0
	v_mov_b32_e32 v110, v0
	v_mov_b32_e32 v111, v0
	v_mov_b32_e32 v120, v0
	v_mov_b32_e32 v121, v0
	v_mov_b32_e32 v122, v0
	v_mov_b32_e32 v123, v0
	v_mov_b32_e32 v124, v0
	v_mov_b32_e32 v125, v0
	v_mov_b32_e32 v126, v0
	v_mov_b32_e32 v127, v0
	s_branch .LBB0_1332

.LBB0_1435:
	ds_read_b128 v[128:131], v180
	ds_read_b128 v[132:135], v180 offset:1024
	ds_read_b128 v[136:139], v180 offset:2048
	ds_read_b128 v[140:143], v180 offset:3072
	ds_read_b128 v[144:147], v181
	ds_read_b128 v[148:151], v181 offset:1024
	ds_read_b128 v[170:173], v181 offset:2048
	ds_read_b128 v[174:177], v181 offset:3072
	s_add_u32 s26, s24, 0xfffc0080
	s_addc_u32 s27, s25, -1
	s_cmp_eq_u32 s35, 12
	s_cselect_b32 s29, s1, s27
	s_cselect_b32 s28, s19, s26
	s_cselect_b32 s27, s17, s34
	s_cselect_b32 s26, s30, s31
	v_lshl_add_u64 v[184:185], s[24:25], 0, v[162:163]
	s_add_i32 m0, s40, 0xc000
	s_nop 0
	global_load_lds_dwordx4 v[184:185], off
	v_lshl_add_u64 v[184:185], s[24:25], 0, v[164:165]
	s_add_i32 m0, s40, 0xe000
	s_nop 0
	global_load_lds_dwordx4 v[184:185], off
	ds_read_b128 v[184:187], v182
	ds_read_b128 v[188:191], v182 offset:1024
	ds_read_b128 v[192:195], v182 offset:2048
	ds_read_b128 v[196:199], v182 offset:3072
	ds_read_b128 v[200:203], v182 offset:4096
	ds_read_b128 v[204:207], v182 offset:5120
	ds_read_b128 v[208:211], v182 offset:6144
	ds_read_b128 v[212:215], v182 offset:7168
	s_waitcnt vmcnt(8)
	s_waitcnt lgkmcnt(0)
	s_barrier
	s_setprio 1
	s_waitcnt lgkmcnt(0)
	v_mfma_f32_16x16x32_bf16 v[124:127], v[128:131], v[184:187], v[124:127]
	v_mfma_f32_16x16x32_bf16 v[124:127], v[132:135], v[188:191], v[124:127]
	v_mfma_f32_16x16x32_bf16 v[120:123], v[136:139], v[184:187], v[120:123]
	v_mfma_f32_16x16x32_bf16 v[120:123], v[140:143], v[188:191], v[120:123]
	v_mfma_f32_16x16x32_bf16 v[108:111], v[128:131], v[192:195], v[108:111]
	v_mfma_f32_16x16x32_bf16 v[108:111], v[132:135], v[196:199], v[108:111]
	v_mfma_f32_16x16x32_bf16 v[104:107], v[136:139], v[192:195], v[104:107]
	v_mfma_f32_16x16x32_bf16 v[104:107], v[140:143], v[196:199], v[104:107]
	v_mfma_f32_16x16x32_bf16 v[92:95], v[128:131], v[200:203], v[92:95]
	v_mfma_f32_16x16x32_bf16 v[92:95], v[132:135], v[204:207], v[92:95]
	v_mfma_f32_16x16x32_bf16 v[88:91], v[136:139], v[200:203], v[88:91]
	v_mfma_f32_16x16x32_bf16 v[88:91], v[140:143], v[204:207], v[88:91]
	v_mfma_f32_16x16x32_bf16 v[76:79], v[128:131], v[208:211], v[76:79]
	v_mfma_f32_16x16x32_bf16 v[76:79], v[132:135], v[212:215], v[76:79]
	v_mfma_f32_16x16x32_bf16 v[72:75], v[136:139], v[208:211], v[72:75]
	v_mfma_f32_16x16x32_bf16 v[72:75], v[140:143], v[212:215], v[72:75]
	s_setprio 0
	s_setprio 1
	v_mfma_f32_16x16x32_bf16 v[116:119], v[144:147], v[184:187], v[116:119]
	v_mfma_f32_16x16x32_bf16 v[116:119], v[148:151], v[188:191], v[116:119]
	v_mfma_f32_16x16x32_bf16 v[112:115], v[170:173], v[184:187], v[112:115]
	v_mfma_f32_16x16x32_bf16 v[112:115], v[174:177], v[188:191], v[112:115]
	v_mfma_f32_16x16x32_bf16 v[100:103], v[144:147], v[192:195], v[100:103]
	v_mfma_f32_16x16x32_bf16 v[100:103], v[148:151], v[196:199], v[100:103]
	v_mfma_f32_16x16x32_bf16 v[96:99], v[170:173], v[192:195], v[96:99]
	v_mfma_f32_16x16x32_bf16 v[96:99], v[174:177], v[196:199], v[96:99]
	v_mfma_f32_16x16x32_bf16 v[84:87], v[144:147], v[200:203], v[84:87]
	v_mfma_f32_16x16x32_bf16 v[84:87], v[148:151], v[204:207], v[84:87]
	v_mfma_f32_16x16x32_bf16 v[80:83], v[170:173], v[200:203], v[80:83]
	v_mfma_f32_16x16x32_bf16 v[80:83], v[174:177], v[204:207], v[80:83]
	v_mfma_f32_16x16x32_bf16 v[68:71], v[144:147], v[208:211], v[68:71]
	v_mfma_f32_16x16x32_bf16 v[68:71], v[148:151], v[212:215], v[68:71]
	v_mfma_f32_16x16x32_bf16 v[64:67], v[170:173], v[208:211], v[64:67]
	v_mfma_f32_16x16x32_bf16 v[64:67], v[174:177], v[212:215], v[64:67]
	s_setprio 0
	s_barrier
	s_add_i32 s54, s50, s39
	v_lshl_add_u64 v[216:217], s[26:27], 0, v[154:155]
	s_mov_b32 m0, s54
	v_lshl_add_u64 v[218:219], s[26:27], 0, v[158:159]
	global_load_lds_dwordx4 v[216:217], off
	s_add_i32 m0, s54, 0x2000
	s_add_u32 s54, s26, 0x100000
	s_addc_u32 s55, s27, 0
	s_add_i32 s56, s51, s39
	global_load_lds_dwordx4 v[218:219], off
	v_lshl_add_u64 v[184:185], s[54:55], 0, v[154:155]
	s_mov_b32 m0, s56
	v_lshl_add_u64 v[220:221], s[28:29], 0, v[152:153]
	global_load_lds_dwordx4 v[184:185], off
	v_lshl_add_u64 v[184:185], s[54:55], 0, v[158:159]
	s_add_i32 m0, s56, 0x2000
	v_lshl_add_u64 v[222:223], s[28:29], 0, v[156:157]
	global_load_lds_dwordx4 v[184:185], off
	s_mov_b32 m0, s40
	s_nop 0
	global_load_lds_dwordx4 v[220:221], off
	s_mov_b32 m0, s41
	s_nop 0
	global_load_lds_dwordx4 v[222:223], off
	ds_read_b128 v[184:187], v182 offset:16384
	ds_read_b128 v[188:191], v182 offset:17408
	ds_read_b128 v[192:195], v182 offset:18432
	ds_read_b128 v[196:199], v182 offset:19456
	ds_read_b128 v[200:203], v182 offset:20480
	ds_read_b128 v[204:207], v182 offset:21504
	ds_read_b128 v[208:211], v182 offset:22528
	ds_read_b128 v[212:215], v182 offset:23552
	s_waitcnt vmcnt(8)
	s_waitcnt lgkmcnt(0)
	s_barrier
	s_setprio 1
	s_waitcnt lgkmcnt(0)
	v_mfma_f32_16x16x32_bf16 v[60:63], v[128:131], v[184:187], v[60:63]
	v_mfma_f32_16x16x32_bf16 v[60:63], v[132:135], v[188:191], v[60:63]
	v_mfma_f32_16x16x32_bf16 v[56:59], v[136:139], v[184:187], v[56:59]
	v_mfma_f32_16x16x32_bf16 v[56:59], v[140:143], v[188:191], v[56:59]
	v_mfma_f32_16x16x32_bf16 v[44:47], v[128:131], v[192:195], v[44:47]
	v_mfma_f32_16x16x32_bf16 v[44:47], v[132:135], v[196:199], v[44:47]
	v_mfma_f32_16x16x32_bf16 v[40:43], v[136:139], v[192:195], v[40:43]
	v_mfma_f32_16x16x32_bf16 v[40:43], v[140:143], v[196:199], v[40:43]
	v_mfma_f32_16x16x32_bf16 v[28:31], v[128:131], v[200:203], v[28:31]
	v_mfma_f32_16x16x32_bf16 v[28:31], v[132:135], v[204:207], v[28:31]
	v_mfma_f32_16x16x32_bf16 v[24:27], v[136:139], v[200:203], v[24:27]
	v_mfma_f32_16x16x32_bf16 v[24:27], v[140:143], v[204:207], v[24:27]
	v_mfma_f32_16x16x32_bf16 v[12:15], v[128:131], v[208:211], v[12:15]
	v_mfma_f32_16x16x32_bf16 v[12:15], v[132:135], v[212:215], v[12:15]
	v_mfma_f32_16x16x32_bf16 v[8:11], v[136:139], v[208:211], v[8:11]
	v_mfma_f32_16x16x32_bf16 v[8:11], v[140:143], v[212:215], v[8:11]
	s_setprio 0
	s_setprio 1
	v_mfma_f32_16x16x32_bf16 v[52:55], v[144:147], v[184:187], v[52:55]
	v_mfma_f32_16x16x32_bf16 v[52:55], v[148:151], v[188:191], v[52:55]
	v_mfma_f32_16x16x32_bf16 v[48:51], v[170:173], v[184:187], v[48:51]
	v_mfma_f32_16x16x32_bf16 v[48:51], v[174:177], v[188:191], v[48:51]
	v_mfma_f32_16x16x32_bf16 v[36:39], v[144:147], v[192:195], v[36:39]
	v_mfma_f32_16x16x32_bf16 v[36:39], v[148:151], v[196:199], v[36:39]
	v_mfma_f32_16x16x32_bf16 v[32:35], v[170:173], v[192:195], v[32:35]
	v_mfma_f32_16x16x32_bf16 v[32:35], v[174:177], v[196:199], v[32:35]
	v_mfma_f32_16x16x32_bf16 v[20:23], v[144:147], v[200:203], v[20:23]
	v_mfma_f32_16x16x32_bf16 v[20:23], v[148:151], v[204:207], v[20:23]
	v_mfma_f32_16x16x32_bf16 v[16:19], v[170:173], v[200:203], v[16:19]
	v_mfma_f32_16x16x32_bf16 v[16:19], v[174:177], v[204:207], v[16:19]
	v_mfma_f32_16x16x32_bf16 v[4:7], v[144:147], v[208:211], v[4:7]
	v_mfma_f32_16x16x32_bf16 v[4:7], v[148:151], v[212:215], v[4:7]
	v_mfma_f32_16x16x32_bf16 v[0:3], v[170:173], v[208:211], v[0:3]
	v_mfma_f32_16x16x32_bf16 v[0:3], v[174:177], v[212:215], v[0:3]
	s_setprio 0
	s_barrier
	s_add_i32 s54, 0, 0x18000
	s_add_i32 s55, 0, 0x1c000
	v_add_u32_e32 v140, s54, v178
	v_add_u32_e32 v174, s55, v178
	ds_read_b128 v[128:131], v140
	ds_read_b128 v[132:135], v140 offset:1024
	ds_read_b128 v[136:139], v140 offset:2048
	ds_read_b128 v[140:143], v140 offset:3072
	ds_read_b128 v[144:147], v174
	ds_read_b128 v[148:151], v174 offset:1024
	ds_read_b128 v[170:173], v174 offset:2048
	ds_read_b128 v[174:177], v174 offset:3072
	s_add_u32 s28, s28, 0x40000
	s_addc_u32 s29, s29, 0
	s_mov_b32 m0, s42
	v_lshl_add_u64 v[184:185], s[28:29], 0, v[152:153]
	global_load_lds_dwordx4 v[184:185], off
	v_lshl_add_u64 v[184:185], s[28:29], 0, v[156:157]
	s_mov_b32 m0, s43
	s_nop 0
	global_load_lds_dwordx4 v[184:185], off
	ds_read_b128 v[184:187], v182 offset:32768
	ds_read_b128 v[188:191], v182 offset:33792
	ds_read_b128 v[192:195], v182 offset:34816
	ds_read_b128 v[196:199], v182 offset:35840
	ds_read_b128 v[200:203], v182 offset:36864
	ds_read_b128 v[204:207], v182 offset:37888
	ds_read_b128 v[208:211], v182 offset:38912
	ds_read_b128 v[212:215], v182 offset:39936
	s_waitcnt vmcnt(8)
	s_waitcnt lgkmcnt(0)
	s_barrier
	s_setprio 1
	s_waitcnt lgkmcnt(0)
	v_mfma_f32_16x16x32_bf16 v[124:127], v[128:131], v[184:187], v[124:127]
	v_mfma_f32_16x16x32_bf16 v[124:127], v[132:135], v[188:191], v[124:127]
	v_mfma_f32_16x16x32_bf16 v[120:123], v[136:139], v[184:187], v[120:123]
	v_mfma_f32_16x16x32_bf16 v[120:123], v[140:143], v[188:191], v[120:123]
	v_mfma_f32_16x16x32_bf16 v[108:111], v[128:131], v[192:195], v[108:111]
	v_mfma_f32_16x16x32_bf16 v[108:111], v[132:135], v[196:199], v[108:111]
	v_mfma_f32_16x16x32_bf16 v[104:107], v[136:139], v[192:195], v[104:107]
	v_mfma_f32_16x16x32_bf16 v[104:107], v[140:143], v[196:199], v[104:107]
	v_mfma_f32_16x16x32_bf16 v[92:95], v[128:131], v[200:203], v[92:95]
	v_mfma_f32_16x16x32_bf16 v[92:95], v[132:135], v[204:207], v[92:95]
	v_mfma_f32_16x16x32_bf16 v[88:91], v[136:139], v[200:203], v[88:91]
	v_mfma_f32_16x16x32_bf16 v[88:91], v[140:143], v[204:207], v[88:91]
	v_mfma_f32_16x16x32_bf16 v[76:79], v[128:131], v[208:211], v[76:79]
	v_mfma_f32_16x16x32_bf16 v[76:79], v[132:135], v[212:215], v[76:79]
	v_mfma_f32_16x16x32_bf16 v[72:75], v[136:139], v[208:211], v[72:75]
	v_mfma_f32_16x16x32_bf16 v[72:75], v[140:143], v[212:215], v[72:75]
	s_setprio 0
	s_setprio 1
	v_mfma_f32_16x16x32_bf16 v[116:119], v[144:147], v[184:187], v[116:119]
	v_mfma_f32_16x16x32_bf16 v[116:119], v[148:151], v[188:191], v[116:119]
	v_mfma_f32_16x16x32_bf16 v[112:115], v[170:173], v[184:187], v[112:115]
	v_mfma_f32_16x16x32_bf16 v[112:115], v[174:177], v[188:191], v[112:115]
	v_mfma_f32_16x16x32_bf16 v[100:103], v[144:147], v[192:195], v[100:103]
	v_mfma_f32_16x16x32_bf16 v[100:103], v[148:151], v[196:199], v[100:103]
	v_mfma_f32_16x16x32_bf16 v[96:99], v[170:173], v[192:195], v[96:99]
	v_mfma_f32_16x16x32_bf16 v[96:99], v[174:177], v[196:199], v[96:99]
	v_mfma_f32_16x16x32_bf16 v[84:87], v[144:147], v[200:203], v[84:87]
	v_mfma_f32_16x16x32_bf16 v[84:87], v[148:151], v[204:207], v[84:87]
	v_mfma_f32_16x16x32_bf16 v[80:83], v[170:173], v[200:203], v[80:83]
	v_mfma_f32_16x16x32_bf16 v[80:83], v[174:177], v[204:207], v[80:83]
	v_mfma_f32_16x16x32_bf16 v[68:71], v[144:147], v[208:211], v[68:71]
	v_mfma_f32_16x16x32_bf16 v[68:71], v[148:151], v[212:215], v[68:71]
	v_mfma_f32_16x16x32_bf16 v[64:67], v[170:173], v[208:211], v[64:67]
	v_mfma_f32_16x16x32_bf16 v[64:67], v[174:177], v[212:215], v[64:67]
	s_setprio 0
	s_barrier
	s_add_i32 s28, s54, s39
	v_lshl_add_u64 v[184:185], v[216:217], 0, s[14:15]
	s_mov_b32 m0, s28
	s_nop 0
	global_load_lds_dwordx4 v[184:185], off
	s_add_i32 m0, s28, 0x2000
	s_add_u32 s26, s26, 0x100080
	v_lshl_add_u64 v[184:185], v[218:219], 0, s[14:15]
	s_addc_u32 s27, s27, 0
	s_add_i32 s28, s55, s39
	global_load_lds_dwordx4 v[184:185], off
	v_lshl_add_u64 v[184:185], s[26:27], 0, v[154:155]
	s_mov_b32 m0, s28
	s_nop 0
	global_load_lds_dwordx4 v[184:185], off
	v_lshl_add_u64 v[184:185], s[26:27], 0, v[158:159]
	s_add_i32 m0, s28, 0x2000
	s_nop 0
	global_load_lds_dwordx4 v[184:185], off
	v_lshl_add_u64 v[184:185], v[220:221], 0, s[14:15]
	s_mov_b32 m0, s45
	s_nop 0
	global_load_lds_dwordx4 v[184:185], off
	v_lshl_add_u64 v[184:185], v[222:223], 0, s[14:15]
	s_mov_b32 m0, s46
	s_nop 0
	global_load_lds_dwordx4 v[184:185], off
	ds_read_b128 v[184:187], v182 offset:49152
	ds_read_b128 v[188:191], v182 offset:50176
	ds_read_b128 v[192:195], v182 offset:51200
	ds_read_b128 v[196:199], v182 offset:52224
	ds_read_b128 v[200:203], v182 offset:53248
	ds_read_b128 v[204:207], v182 offset:54272
	ds_read_b128 v[208:211], v182 offset:55296
	ds_read_b128 v[212:215], v182 offset:56320
	s_waitcnt vmcnt(8)
	s_waitcnt lgkmcnt(0)
	s_barrier
	s_setprio 1
	s_waitcnt lgkmcnt(0)
	v_mfma_f32_16x16x32_bf16 v[60:63], v[128:131], v[184:187], v[60:63]
	v_mfma_f32_16x16x32_bf16 v[60:63], v[132:135], v[188:191], v[60:63]
	v_mfma_f32_16x16x32_bf16 v[56:59], v[136:139], v[184:187], v[56:59]
	v_mfma_f32_16x16x32_bf16 v[56:59], v[140:143], v[188:191], v[56:59]
	v_mfma_f32_16x16x32_bf16 v[44:47], v[128:131], v[192:195], v[44:47]
	v_mfma_f32_16x16x32_bf16 v[44:47], v[132:135], v[196:199], v[44:47]
	v_mfma_f32_16x16x32_bf16 v[40:43], v[136:139], v[192:195], v[40:43]
	v_mfma_f32_16x16x32_bf16 v[40:43], v[140:143], v[196:199], v[40:43]
	v_mfma_f32_16x16x32_bf16 v[28:31], v[128:131], v[200:203], v[28:31]
	v_mfma_f32_16x16x32_bf16 v[28:31], v[132:135], v[204:207], v[28:31]
	v_mfma_f32_16x16x32_bf16 v[24:27], v[136:139], v[200:203], v[24:27]
	v_mfma_f32_16x16x32_bf16 v[24:27], v[140:143], v[204:207], v[24:27]
	v_mfma_f32_16x16x32_bf16 v[12:15], v[128:131], v[208:211], v[12:15]
	v_mfma_f32_16x16x32_bf16 v[12:15], v[132:135], v[212:215], v[12:15]
	v_mfma_f32_16x16x32_bf16 v[8:11], v[136:139], v[208:211], v[8:11]
	v_mfma_f32_16x16x32_bf16 v[8:11], v[140:143], v[212:215], v[8:11]
	s_setprio 0
	s_setprio 1
	v_mfma_f32_16x16x32_bf16 v[52:55], v[144:147], v[184:187], v[52:55]
	v_mfma_f32_16x16x32_bf16 v[52:55], v[148:151], v[188:191], v[52:55]
	v_mfma_f32_16x16x32_bf16 v[48:51], v[170:173], v[184:187], v[48:51]
	v_mfma_f32_16x16x32_bf16 v[48:51], v[174:177], v[188:191], v[48:51]
	v_mfma_f32_16x16x32_bf16 v[36:39], v[144:147], v[192:195], v[36:39]
	v_mfma_f32_16x16x32_bf16 v[36:39], v[148:151], v[196:199], v[36:39]
	v_mfma_f32_16x16x32_bf16 v[32:35], v[170:173], v[192:195], v[32:35]
	v_mfma_f32_16x16x32_bf16 v[32:35], v[174:177], v[196:199], v[32:35]
	v_mfma_f32_16x16x32_bf16 v[20:23], v[144:147], v[200:203], v[20:23]
	v_mfma_f32_16x16x32_bf16 v[20:23], v[148:151], v[204:207], v[20:23]
	v_mfma_f32_16x16x32_bf16 v[16:19], v[170:173], v[200:203], v[16:19]
	v_mfma_f32_16x16x32_bf16 v[16:19], v[174:177], v[204:207], v[16:19]
	v_mfma_f32_16x16x32_bf16 v[4:7], v[144:147], v[208:211], v[4:7]
	v_mfma_f32_16x16x32_bf16 v[4:7], v[148:151], v[212:215], v[4:7]
	v_mfma_f32_16x16x32_bf16 v[0:3], v[170:173], v[208:211], v[0:3]
	v_mfma_f32_16x16x32_bf16 v[0:3], v[174:177], v[212:215], v[0:3]
	s_setprio 0
	s_barrier
	s_add_i32 s35, s35, 2
	s_add_u32 s24, s24, 0x100
	s_addc_u32 s25, s25, 0
	s_add_u32 s31, s31, 0x100
	s_addc_u32 s34, s34, 0
	s_cmp_gt_u32 s35, 13
	s_cbranch_scc0 .LBB0_1435
	s_and_b64 vcc, exec, s[8:9]
	s_cbranch_vccz .LBB0_1438
	s_barrier

.LBB0_1543:
	ds_read_b128 v[128:131], v167
	ds_read_b128 v[154:157], v167 offset:1024
	ds_read_b128 v[172:175], v167 offset:2048
	ds_read_b128 v[176:179], v167 offset:3072
	ds_read_b128 v[180:183], v168
	ds_read_b128 v[184:187], v168 offset:1024
	ds_read_b128 v[188:191], v168 offset:2048
	ds_read_b128 v[192:195], v168 offset:3072
	s_add_u32 s22, s20, 0x1000
	s_addc_u32 s23, s21, 0
	s_cmp_eq_u32 s54, 60
	s_cselect_b32 s27, s13, s23
	s_cselect_b32 s26, s50, s22
	s_cselect_b32 s25, s11, s53
	s_cselect_b32 s24, s51, s52
	v_lshl_add_u64 v[160:161], s[20:21], 0, v[144:145]
	s_add_i32 m0, s19, 0xc000
	s_nop 0
	global_load_lds_dwordx4 v[160:161], off
	v_lshl_add_u64 v[160:161], s[20:21], 0, v[146:147]
	s_add_i32 m0, s19, 0xe000
	s_nop 0
	global_load_lds_dwordx4 v[160:161], off
	ds_read_b128 v[196:199], v169
	ds_read_b128 v[200:203], v169 offset:1024
	ds_read_b128 v[204:207], v169 offset:2048
	ds_read_b128 v[208:211], v169 offset:3072
	ds_read_b128 v[212:215], v169 offset:4096
	ds_read_b128 v[216:219], v169 offset:5120
	ds_read_b128 v[220:223], v169 offset:6144
	ds_read_b128 v[224:227], v169 offset:7168
	s_waitcnt vmcnt(8)
	s_waitcnt lgkmcnt(0)
	s_barrier
	s_setprio 1
	s_waitcnt lgkmcnt(0)
	v_mfma_f32_16x16x32_bf16 v[124:127], v[128:131], v[196:199], v[124:127]
	v_mfma_f32_16x16x32_bf16 v[124:127], v[154:157], v[200:203], v[124:127]
	v_mfma_f32_16x16x32_bf16 v[120:123], v[172:175], v[196:199], v[120:123]
	v_mfma_f32_16x16x32_bf16 v[120:123], v[176:179], v[200:203], v[120:123]
	v_mfma_f32_16x16x32_bf16 v[108:111], v[128:131], v[204:207], v[108:111]
	v_mfma_f32_16x16x32_bf16 v[108:111], v[154:157], v[208:211], v[108:111]
	v_mfma_f32_16x16x32_bf16 v[104:107], v[172:175], v[204:207], v[104:107]
	v_mfma_f32_16x16x32_bf16 v[104:107], v[176:179], v[208:211], v[104:107]
	v_mfma_f32_16x16x32_bf16 v[92:95], v[128:131], v[212:215], v[92:95]
	v_mfma_f32_16x16x32_bf16 v[92:95], v[154:157], v[216:219], v[92:95]
	v_mfma_f32_16x16x32_bf16 v[88:91], v[172:175], v[212:215], v[88:91]
	v_mfma_f32_16x16x32_bf16 v[88:91], v[176:179], v[216:219], v[88:91]
	v_mfma_f32_16x16x32_bf16 v[76:79], v[128:131], v[220:223], v[76:79]
	v_mfma_f32_16x16x32_bf16 v[76:79], v[154:157], v[224:227], v[76:79]
	v_mfma_f32_16x16x32_bf16 v[72:75], v[172:175], v[220:223], v[72:75]
	v_mfma_f32_16x16x32_bf16 v[72:75], v[176:179], v[224:227], v[72:75]
	s_setprio 0
	s_setprio 1
	v_mfma_f32_16x16x32_bf16 v[116:119], v[180:183], v[196:199], v[116:119]
	v_mfma_f32_16x16x32_bf16 v[116:119], v[184:187], v[200:203], v[116:119]
	v_mfma_f32_16x16x32_bf16 v[112:115], v[188:191], v[196:199], v[112:115]
	v_mfma_f32_16x16x32_bf16 v[112:115], v[192:195], v[200:203], v[112:115]
	v_mfma_f32_16x16x32_bf16 v[100:103], v[180:183], v[204:207], v[100:103]
	v_mfma_f32_16x16x32_bf16 v[100:103], v[184:187], v[208:211], v[100:103]
	v_mfma_f32_16x16x32_bf16 v[96:99], v[188:191], v[204:207], v[96:99]
	v_mfma_f32_16x16x32_bf16 v[96:99], v[192:195], v[208:211], v[96:99]
	v_mfma_f32_16x16x32_bf16 v[84:87], v[180:183], v[212:215], v[84:87]
	v_mfma_f32_16x16x32_bf16 v[84:87], v[184:187], v[216:219], v[84:87]
	v_mfma_f32_16x16x32_bf16 v[80:83], v[188:191], v[212:215], v[80:83]
	v_mfma_f32_16x16x32_bf16 v[80:83], v[192:195], v[216:219], v[80:83]
	v_mfma_f32_16x16x32_bf16 v[68:71], v[180:183], v[220:223], v[68:71]
	v_mfma_f32_16x16x32_bf16 v[68:71], v[184:187], v[224:227], v[68:71]
	v_mfma_f32_16x16x32_bf16 v[64:67], v[188:191], v[220:223], v[64:67]
	v_mfma_f32_16x16x32_bf16 v[64:67], v[192:195], v[224:227], v[64:67]
	s_setprio 0
	s_barrier
	s_add_i32 s20, s45, s30
	v_lshl_add_u64 v[160:161], s[24:25], 0, v[134:135]
	s_mov_b32 m0, s20
	v_lshl_add_u64 v[164:165], s[24:25], 0, v[138:139]
	global_load_lds_dwordx4 v[160:161], off
	s_add_i32 m0, s20, 0x2000
	s_add_u32 s20, s24, 0x100000
	s_addc_u32 s21, s25, 0
	s_add_i32 s55, s46, s30
	global_load_lds_dwordx4 v[164:165], off
	v_lshl_add_u64 v[196:197], s[20:21], 0, v[134:135]
	s_mov_b32 m0, s55
	v_lshl_add_u64 v[228:229], s[26:27], 0, v[132:133]
	global_load_lds_dwordx4 v[196:197], off
	v_lshl_add_u64 v[196:197], s[20:21], 0, v[138:139]
	s_add_i32 m0, s55, 0x2000
	v_lshl_add_u64 v[230:231], s[26:27], 0, v[136:137]
	global_load_lds_dwordx4 v[196:197], off
	s_mov_b32 m0, s19
	s_nop 0
	global_load_lds_dwordx4 v[228:229], off
	s_mov_b32 m0, s36
	s_nop 0
	global_load_lds_dwordx4 v[230:231], off
	ds_read_b128 v[196:199], v169 offset:16384
	ds_read_b128 v[200:203], v169 offset:17408
	ds_read_b128 v[204:207], v169 offset:18432
	ds_read_b128 v[208:211], v169 offset:19456
	ds_read_b128 v[212:215], v169 offset:20480
	ds_read_b128 v[216:219], v169 offset:21504
	ds_read_b128 v[220:223], v169 offset:22528
	ds_read_b128 v[224:227], v169 offset:23552
	s_waitcnt vmcnt(8)
	s_waitcnt lgkmcnt(0)
	s_barrier
	s_setprio 1
	s_waitcnt lgkmcnt(0)
	v_mfma_f32_16x16x32_bf16 v[60:63], v[128:131], v[196:199], v[60:63]
	v_mfma_f32_16x16x32_bf16 v[60:63], v[154:157], v[200:203], v[60:63]
	v_mfma_f32_16x16x32_bf16 v[56:59], v[172:175], v[196:199], v[56:59]
	v_mfma_f32_16x16x32_bf16 v[56:59], v[176:179], v[200:203], v[56:59]
	v_mfma_f32_16x16x32_bf16 v[44:47], v[128:131], v[204:207], v[44:47]
	v_mfma_f32_16x16x32_bf16 v[44:47], v[154:157], v[208:211], v[44:47]
	v_mfma_f32_16x16x32_bf16 v[40:43], v[172:175], v[204:207], v[40:43]
	v_mfma_f32_16x16x32_bf16 v[40:43], v[176:179], v[208:211], v[40:43]
	v_mfma_f32_16x16x32_bf16 v[28:31], v[128:131], v[212:215], v[28:31]
	v_mfma_f32_16x16x32_bf16 v[28:31], v[154:157], v[216:219], v[28:31]
	v_mfma_f32_16x16x32_bf16 v[24:27], v[172:175], v[212:215], v[24:27]
	v_mfma_f32_16x16x32_bf16 v[24:27], v[176:179], v[216:219], v[24:27]
	v_mfma_f32_16x16x32_bf16 v[12:15], v[128:131], v[220:223], v[12:15]
	v_mfma_f32_16x16x32_bf16 v[12:15], v[154:157], v[224:227], v[12:15]
	v_mfma_f32_16x16x32_bf16 v[8:11], v[172:175], v[220:223], v[8:11]
	v_mfma_f32_16x16x32_bf16 v[8:11], v[176:179], v[224:227], v[8:11]
	s_setprio 0
	s_setprio 1
	v_mfma_f32_16x16x32_bf16 v[52:55], v[180:183], v[196:199], v[52:55]
	v_mfma_f32_16x16x32_bf16 v[52:55], v[184:187], v[200:203], v[52:55]
	v_mfma_f32_16x16x32_bf16 v[48:51], v[188:191], v[196:199], v[48:51]
	v_mfma_f32_16x16x32_bf16 v[48:51], v[192:195], v[200:203], v[48:51]
	v_mfma_f32_16x16x32_bf16 v[36:39], v[180:183], v[204:207], v[36:39]
	v_mfma_f32_16x16x32_bf16 v[36:39], v[184:187], v[208:211], v[36:39]
	v_mfma_f32_16x16x32_bf16 v[32:35], v[188:191], v[204:207], v[32:35]
	v_mfma_f32_16x16x32_bf16 v[32:35], v[192:195], v[208:211], v[32:35]
	v_mfma_f32_16x16x32_bf16 v[20:23], v[180:183], v[212:215], v[20:23]
	v_mfma_f32_16x16x32_bf16 v[20:23], v[184:187], v[216:219], v[20:23]
	v_mfma_f32_16x16x32_bf16 v[16:19], v[188:191], v[212:215], v[16:19]
	v_mfma_f32_16x16x32_bf16 v[16:19], v[192:195], v[216:219], v[16:19]
	v_mfma_f32_16x16x32_bf16 v[4:7], v[180:183], v[220:223], v[4:7]
	v_mfma_f32_16x16x32_bf16 v[4:7], v[184:187], v[224:227], v[4:7]
	v_mfma_f32_16x16x32_bf16 v[0:3], v[188:191], v[220:223], v[0:3]
	v_mfma_f32_16x16x32_bf16 v[0:3], v[192:195], v[224:227], v[0:3]
	s_setprio 0
	s_barrier
	s_add_i32 s55, 0, 0x18000
	v_add_u32_e32 v153, s55, v159
	s_add_i32 s56, 0, 0x1c000
	ds_read_b128 v[128:131], v153
	ds_read_b128 v[154:157], v153 offset:1024
	ds_read_b128 v[172:175], v153 offset:2048
	ds_read_b128 v[176:179], v153 offset:3072
	v_add_u32_e32 v153, s56, v159
	ds_read_b128 v[180:183], v153
	ds_read_b128 v[184:187], v153 offset:1024
	ds_read_b128 v[188:191], v153 offset:2048
	ds_read_b128 v[192:195], v153 offset:3072
	s_add_u32 s20, s26, 0x100000
	s_addc_u32 s21, s27, 0
	s_mov_b32 m0, s37
	v_lshl_add_u64 v[196:197], s[20:21], 0, v[132:133]
	global_load_lds_dwordx4 v[196:197], off
	v_lshl_add_u64 v[196:197], s[20:21], 0, v[136:137]
	s_mov_b32 m0, s38
	s_nop 0
	global_load_lds_dwordx4 v[196:197], off
	ds_read_b128 v[196:199], v169 offset:32768
	ds_read_b128 v[200:203], v169 offset:33792
	ds_read_b128 v[204:207], v169 offset:34816
	ds_read_b128 v[208:211], v169 offset:35840
	ds_read_b128 v[212:215], v169 offset:36864
	ds_read_b128 v[216:219], v169 offset:37888
	ds_read_b128 v[220:223], v169 offset:38912
	ds_read_b128 v[224:227], v169 offset:39936
	s_waitcnt vmcnt(8)
	s_waitcnt lgkmcnt(0)
	s_barrier
	s_setprio 1
	s_waitcnt lgkmcnt(0)
	v_mfma_f32_16x16x32_bf16 v[124:127], v[128:131], v[196:199], v[124:127]
	v_mfma_f32_16x16x32_bf16 v[124:127], v[154:157], v[200:203], v[124:127]
	v_mfma_f32_16x16x32_bf16 v[120:123], v[172:175], v[196:199], v[120:123]
	v_mfma_f32_16x16x32_bf16 v[120:123], v[176:179], v[200:203], v[120:123]
	v_mfma_f32_16x16x32_bf16 v[108:111], v[128:131], v[204:207], v[108:111]
	v_mfma_f32_16x16x32_bf16 v[108:111], v[154:157], v[208:211], v[108:111]
	v_mfma_f32_16x16x32_bf16 v[104:107], v[172:175], v[204:207], v[104:107]
	v_mfma_f32_16x16x32_bf16 v[104:107], v[176:179], v[208:211], v[104:107]
	v_mfma_f32_16x16x32_bf16 v[92:95], v[128:131], v[212:215], v[92:95]
	v_mfma_f32_16x16x32_bf16 v[92:95], v[154:157], v[216:219], v[92:95]
	v_mfma_f32_16x16x32_bf16 v[88:91], v[172:175], v[212:215], v[88:91]
	v_mfma_f32_16x16x32_bf16 v[88:91], v[176:179], v[216:219], v[88:91]
	v_mfma_f32_16x16x32_bf16 v[76:79], v[128:131], v[220:223], v[76:79]
	v_mfma_f32_16x16x32_bf16 v[76:79], v[154:157], v[224:227], v[76:79]
	v_mfma_f32_16x16x32_bf16 v[72:75], v[172:175], v[220:223], v[72:75]
	v_mfma_f32_16x16x32_bf16 v[72:75], v[176:179], v[224:227], v[72:75]
	s_setprio 0
	s_setprio 1
	v_mfma_f32_16x16x32_bf16 v[116:119], v[180:183], v[196:199], v[116:119]
	v_mfma_f32_16x16x32_bf16 v[116:119], v[184:187], v[200:203], v[116:119]
	v_mfma_f32_16x16x32_bf16 v[112:115], v[188:191], v[196:199], v[112:115]
	v_mfma_f32_16x16x32_bf16 v[112:115], v[192:195], v[200:203], v[112:115]
	v_mfma_f32_16x16x32_bf16 v[100:103], v[180:183], v[204:207], v[100:103]
	v_mfma_f32_16x16x32_bf16 v[100:103], v[184:187], v[208:211], v[100:103]
	v_mfma_f32_16x16x32_bf16 v[96:99], v[188:191], v[204:207], v[96:99]
	v_mfma_f32_16x16x32_bf16 v[96:99], v[192:195], v[208:211], v[96:99]
	v_mfma_f32_16x16x32_bf16 v[84:87], v[180:183], v[212:215], v[84:87]
	v_mfma_f32_16x16x32_bf16 v[84:87], v[184:187], v[216:219], v[84:87]
	v_mfma_f32_16x16x32_bf16 v[80:83], v[188:191], v[212:215], v[80:83]
	v_mfma_f32_16x16x32_bf16 v[80:83], v[192:195], v[216:219], v[80:83]
	v_mfma_f32_16x16x32_bf16 v[68:71], v[180:183], v[220:223], v[68:71]
	v_mfma_f32_16x16x32_bf16 v[68:71], v[184:187], v[224:227], v[68:71]
	v_mfma_f32_16x16x32_bf16 v[64:67], v[188:191], v[220:223], v[64:67]
	v_mfma_f32_16x16x32_bf16 v[64:67], v[192:195], v[224:227], v[64:67]
	s_setprio 0
	s_barrier
	s_add_i32 s20, s55, s30
	v_lshl_add_u64 v[160:161], v[160:161], 0, s[8:9]
	s_mov_b32 m0, s20
	s_nop 0
	global_load_lds_dwordx4 v[160:161], off
	s_add_i32 m0, s20, 0x2000
	s_add_u32 s20, s24, 0x100800
	v_lshl_add_u64 v[160:161], v[164:165], 0, s[8:9]
	s_addc_u32 s21, s25, 0
	s_add_i32 s24, s56, s30
	global_load_lds_dwordx4 v[160:161], off
	v_lshl_add_u64 v[160:161], s[20:21], 0, v[134:135]
	s_mov_b32 m0, s24
	s_nop 0
	global_load_lds_dwordx4 v[160:161], off
	v_lshl_add_u64 v[160:161], s[20:21], 0, v[138:139]
	s_add_i32 m0, s24, 0x2000
	s_nop 0
	global_load_lds_dwordx4 v[160:161], off
	v_lshl_add_u64 v[160:161], v[228:229], 0, s[8:9]
	s_mov_b32 m0, s41
	s_nop 0
	global_load_lds_dwordx4 v[160:161], off
	v_lshl_add_u64 v[160:161], v[230:231], 0, s[8:9]
	s_mov_b32 m0, s42
	s_nop 0
	global_load_lds_dwordx4 v[160:161], off
	ds_read_b128 v[196:199], v169 offset:49152
	ds_read_b128 v[200:203], v169 offset:50176
	ds_read_b128 v[204:207], v169 offset:51200
	ds_read_b128 v[208:211], v169 offset:52224
	ds_read_b128 v[212:215], v169 offset:53248
	ds_read_b128 v[216:219], v169 offset:54272
	ds_read_b128 v[220:223], v169 offset:55296
	ds_read_b128 v[224:227], v169 offset:56320
	s_waitcnt vmcnt(8)
	s_waitcnt lgkmcnt(0)
	s_barrier
	s_setprio 1
	s_waitcnt lgkmcnt(0)
	v_mfma_f32_16x16x32_bf16 v[60:63], v[128:131], v[196:199], v[60:63]
	v_mfma_f32_16x16x32_bf16 v[60:63], v[154:157], v[200:203], v[60:63]
	v_mfma_f32_16x16x32_bf16 v[56:59], v[172:175], v[196:199], v[56:59]
	v_mfma_f32_16x16x32_bf16 v[56:59], v[176:179], v[200:203], v[56:59]
	v_mfma_f32_16x16x32_bf16 v[44:47], v[128:131], v[204:207], v[44:47]
	v_mfma_f32_16x16x32_bf16 v[44:47], v[154:157], v[208:211], v[44:47]
	v_mfma_f32_16x16x32_bf16 v[40:43], v[172:175], v[204:207], v[40:43]
	v_mfma_f32_16x16x32_bf16 v[40:43], v[176:179], v[208:211], v[40:43]
	v_mfma_f32_16x16x32_bf16 v[28:31], v[128:131], v[212:215], v[28:31]
	v_mfma_f32_16x16x32_bf16 v[28:31], v[154:157], v[216:219], v[28:31]
	v_mfma_f32_16x16x32_bf16 v[24:27], v[172:175], v[212:215], v[24:27]
	v_mfma_f32_16x16x32_bf16 v[24:27], v[176:179], v[216:219], v[24:27]
	v_mfma_f32_16x16x32_bf16 v[12:15], v[128:131], v[220:223], v[12:15]
	v_mfma_f32_16x16x32_bf16 v[12:15], v[154:157], v[224:227], v[12:15]
	v_mfma_f32_16x16x32_bf16 v[8:11], v[172:175], v[220:223], v[8:11]
	v_mfma_f32_16x16x32_bf16 v[8:11], v[176:179], v[224:227], v[8:11]
	s_setprio 0
	s_setprio 1
	v_mfma_f32_16x16x32_bf16 v[52:55], v[180:183], v[196:199], v[52:55]
	v_mfma_f32_16x16x32_bf16 v[52:55], v[184:187], v[200:203], v[52:55]
	v_mfma_f32_16x16x32_bf16 v[48:51], v[188:191], v[196:199], v[48:51]
	v_mfma_f32_16x16x32_bf16 v[48:51], v[192:195], v[200:203], v[48:51]
	v_mfma_f32_16x16x32_bf16 v[36:39], v[180:183], v[204:207], v[36:39]
	v_mfma_f32_16x16x32_bf16 v[36:39], v[184:187], v[208:211], v[36:39]
	v_mfma_f32_16x16x32_bf16 v[32:35], v[188:191], v[204:207], v[32:35]
	v_mfma_f32_16x16x32_bf16 v[32:35], v[192:195], v[208:211], v[32:35]
	v_mfma_f32_16x16x32_bf16 v[20:23], v[180:183], v[212:215], v[20:23]
	v_mfma_f32_16x16x32_bf16 v[20:23], v[184:187], v[216:219], v[20:23]
	v_mfma_f32_16x16x32_bf16 v[16:19], v[188:191], v[212:215], v[16:19]
	v_mfma_f32_16x16x32_bf16 v[16:19], v[192:195], v[216:219], v[16:19]
	v_mfma_f32_16x16x32_bf16 v[4:7], v[180:183], v[220:223], v[4:7]
	v_mfma_f32_16x16x32_bf16 v[4:7], v[184:187], v[224:227], v[4:7]
	v_mfma_f32_16x16x32_bf16 v[0:3], v[188:191], v[220:223], v[0:3]
	v_mfma_f32_16x16x32_bf16 v[0:3], v[192:195], v[224:227], v[0:3]
	s_setprio 0
	s_barrier
	s_add_i32 s54, s54, 2
	s_add_u32 s52, s52, 0x1000
	s_addc_u32 s53, s53, 0
	s_cmp_gt_u32 s54, 61
	s_mov_b64 s[20:21], s[22:23]
	s_cbranch_scc0 .LBB0_1543
	s_and_b64 vcc, exec, s[4:5]
	s_cbranch_vccz .LBB0_1546
	s_barrier

.LBB0_1625:
	ds_read_b128 v[128:131], v177
	ds_read_b128 v[132:135], v177 offset:1024
	ds_read_b128 v[136:139], v177 offset:2048
	ds_read_b128 v[140:143], v177 offset:3072
	ds_read_b128 v[144:147], v178
	ds_read_b128 v[148:151], v178 offset:1024
	ds_read_b128 v[170:173], v178 offset:2048
	ds_read_b128 v[182:185], v178 offset:3072
	s_add_u32 s24, s22, 0xffc00800
	s_addc_u32 s25, s23, -1
	s_cmpk_eq_i32 s57, 0xfc
	s_cselect_b32 s27, s29, s25
	s_cselect_b32 s26, s53, s24
	s_cselect_b32 s25, s17, s56
	s_cselect_b32 s24, s54, s55
	v_lshl_add_u64 v[186:187], s[22:23], 0, v[162:163]
	s_add_i32 m0, s38, 0xc000
	s_nop 0
	global_load_lds_dwordx4 v[186:187], off
	v_lshl_add_u64 v[186:187], s[22:23], 0, v[164:165]
	s_add_i32 m0, s38, 0xe000
	s_nop 0
	global_load_lds_dwordx4 v[186:187], off
	ds_read_b128 v[186:189], v179
	ds_read_b128 v[190:193], v179 offset:1024
	ds_read_b128 v[194:197], v179 offset:2048
	ds_read_b128 v[198:201], v179 offset:3072
	ds_read_b128 v[202:205], v179 offset:4096
	ds_read_b128 v[206:209], v179 offset:5120
	ds_read_b128 v[210:213], v179 offset:6144
	ds_read_b128 v[214:217], v179 offset:7168
	s_waitcnt vmcnt(8)
	s_waitcnt lgkmcnt(0)
	s_barrier
	s_setprio 1
	s_waitcnt lgkmcnt(0)
	v_mfma_f32_16x16x32_bf16 v[124:127], v[128:131], v[186:189], v[124:127]
	v_mfma_f32_16x16x32_bf16 v[124:127], v[132:135], v[190:193], v[124:127]
	v_mfma_f32_16x16x32_bf16 v[120:123], v[136:139], v[186:189], v[120:123]
	v_mfma_f32_16x16x32_bf16 v[120:123], v[140:143], v[190:193], v[120:123]
	v_mfma_f32_16x16x32_bf16 v[108:111], v[128:131], v[194:197], v[108:111]
	v_mfma_f32_16x16x32_bf16 v[108:111], v[132:135], v[198:201], v[108:111]
	v_mfma_f32_16x16x32_bf16 v[104:107], v[136:139], v[194:197], v[104:107]
	v_mfma_f32_16x16x32_bf16 v[104:107], v[140:143], v[198:201], v[104:107]
	v_mfma_f32_16x16x32_bf16 v[92:95], v[128:131], v[202:205], v[92:95]
	v_mfma_f32_16x16x32_bf16 v[92:95], v[132:135], v[206:209], v[92:95]
	v_mfma_f32_16x16x32_bf16 v[88:91], v[136:139], v[202:205], v[88:91]
	v_mfma_f32_16x16x32_bf16 v[88:91], v[140:143], v[206:209], v[88:91]
	v_mfma_f32_16x16x32_bf16 v[76:79], v[128:131], v[210:213], v[76:79]
	v_mfma_f32_16x16x32_bf16 v[76:79], v[132:135], v[214:217], v[76:79]
	v_mfma_f32_16x16x32_bf16 v[72:75], v[136:139], v[210:213], v[72:75]
	v_mfma_f32_16x16x32_bf16 v[72:75], v[140:143], v[214:217], v[72:75]
	s_setprio 0
	s_setprio 1
	v_mfma_f32_16x16x32_bf16 v[116:119], v[144:147], v[186:189], v[116:119]
	v_mfma_f32_16x16x32_bf16 v[116:119], v[148:151], v[190:193], v[116:119]
	v_mfma_f32_16x16x32_bf16 v[112:115], v[170:173], v[186:189], v[112:115]
	v_mfma_f32_16x16x32_bf16 v[112:115], v[182:185], v[190:193], v[112:115]
	v_mfma_f32_16x16x32_bf16 v[100:103], v[144:147], v[194:197], v[100:103]
	v_mfma_f32_16x16x32_bf16 v[100:103], v[148:151], v[198:201], v[100:103]
	v_mfma_f32_16x16x32_bf16 v[96:99], v[170:173], v[194:197], v[96:99]
	v_mfma_f32_16x16x32_bf16 v[96:99], v[182:185], v[198:201], v[96:99]
	v_mfma_f32_16x16x32_bf16 v[84:87], v[144:147], v[202:205], v[84:87]
	v_mfma_f32_16x16x32_bf16 v[84:87], v[148:151], v[206:209], v[84:87]
	v_mfma_f32_16x16x32_bf16 v[80:83], v[170:173], v[202:205], v[80:83]
	v_mfma_f32_16x16x32_bf16 v[80:83], v[182:185], v[206:209], v[80:83]
	v_mfma_f32_16x16x32_bf16 v[68:71], v[144:147], v[210:213], v[68:71]
	v_mfma_f32_16x16x32_bf16 v[68:71], v[148:151], v[214:217], v[68:71]
	v_mfma_f32_16x16x32_bf16 v[64:67], v[170:173], v[210:213], v[64:67]
	v_mfma_f32_16x16x32_bf16 v[64:67], v[182:185], v[214:217], v[64:67]
	s_setprio 0
	s_barrier
	s_add_i32 s58, s48, s37
	v_lshl_add_u64 v[218:219], s[24:25], 0, v[154:155]
	s_mov_b32 m0, s58
	v_lshl_add_u64 v[220:221], s[24:25], 0, v[158:159]
	global_load_lds_dwordx4 v[218:219], off
	s_add_i32 m0, s58, 0x2000
	s_add_u32 s58, s24, 0x400000
	s_addc_u32 s59, s25, 0
	s_add_i32 s60, s49, s37
	global_load_lds_dwordx4 v[220:221], off
	v_lshl_add_u64 v[186:187], s[58:59], 0, v[154:155]
	s_mov_b32 m0, s60
	v_lshl_add_u64 v[222:223], s[26:27], 0, v[152:153]
	global_load_lds_dwordx4 v[186:187], off
	v_lshl_add_u64 v[186:187], s[58:59], 0, v[158:159]
	s_add_i32 m0, s60, 0x2000
	v_lshl_add_u64 v[224:225], s[26:27], 0, v[156:157]
	global_load_lds_dwordx4 v[186:187], off
	s_mov_b32 m0, s38
	s_nop 0
	global_load_lds_dwordx4 v[222:223], off
	s_mov_b32 m0, s39
	s_nop 0
	global_load_lds_dwordx4 v[224:225], off
	ds_read_b128 v[186:189], v179 offset:16384
	ds_read_b128 v[190:193], v179 offset:17408
	ds_read_b128 v[194:197], v179 offset:18432
	ds_read_b128 v[198:201], v179 offset:19456
	ds_read_b128 v[202:205], v179 offset:20480
	ds_read_b128 v[206:209], v179 offset:21504
	ds_read_b128 v[210:213], v179 offset:22528
	ds_read_b128 v[214:217], v179 offset:23552
	s_waitcnt vmcnt(8)
	s_waitcnt lgkmcnt(0)
	s_barrier
	s_setprio 1
	s_waitcnt lgkmcnt(0)
	v_mfma_f32_16x16x32_bf16 v[60:63], v[128:131], v[186:189], v[60:63]
	v_mfma_f32_16x16x32_bf16 v[60:63], v[132:135], v[190:193], v[60:63]
	v_mfma_f32_16x16x32_bf16 v[56:59], v[136:139], v[186:189], v[56:59]
	v_mfma_f32_16x16x32_bf16 v[56:59], v[140:143], v[190:193], v[56:59]
	v_mfma_f32_16x16x32_bf16 v[44:47], v[128:131], v[194:197], v[44:47]
	v_mfma_f32_16x16x32_bf16 v[44:47], v[132:135], v[198:201], v[44:47]
	v_mfma_f32_16x16x32_bf16 v[40:43], v[136:139], v[194:197], v[40:43]
	v_mfma_f32_16x16x32_bf16 v[40:43], v[140:143], v[198:201], v[40:43]
	v_mfma_f32_16x16x32_bf16 v[28:31], v[128:131], v[202:205], v[28:31]
	v_mfma_f32_16x16x32_bf16 v[28:31], v[132:135], v[206:209], v[28:31]
	v_mfma_f32_16x16x32_bf16 v[24:27], v[136:139], v[202:205], v[24:27]
	v_mfma_f32_16x16x32_bf16 v[24:27], v[140:143], v[206:209], v[24:27]
	v_mfma_f32_16x16x32_bf16 v[12:15], v[128:131], v[210:213], v[12:15]
	v_mfma_f32_16x16x32_bf16 v[12:15], v[132:135], v[214:217], v[12:15]
	v_mfma_f32_16x16x32_bf16 v[8:11], v[136:139], v[210:213], v[8:11]
	v_mfma_f32_16x16x32_bf16 v[8:11], v[140:143], v[214:217], v[8:11]
	s_setprio 0
	s_setprio 1
	v_mfma_f32_16x16x32_bf16 v[52:55], v[144:147], v[186:189], v[52:55]
	v_mfma_f32_16x16x32_bf16 v[52:55], v[148:151], v[190:193], v[52:55]
	v_mfma_f32_16x16x32_bf16 v[48:51], v[170:173], v[186:189], v[48:51]
	v_mfma_f32_16x16x32_bf16 v[48:51], v[182:185], v[190:193], v[48:51]
	v_mfma_f32_16x16x32_bf16 v[36:39], v[144:147], v[194:197], v[36:39]
	v_mfma_f32_16x16x32_bf16 v[36:39], v[148:151], v[198:201], v[36:39]
	v_mfma_f32_16x16x32_bf16 v[32:35], v[170:173], v[194:197], v[32:35]
	v_mfma_f32_16x16x32_bf16 v[32:35], v[182:185], v[198:201], v[32:35]
	v_mfma_f32_16x16x32_bf16 v[20:23], v[144:147], v[202:205], v[20:23]
	v_mfma_f32_16x16x32_bf16 v[20:23], v[148:151], v[206:209], v[20:23]
	v_mfma_f32_16x16x32_bf16 v[16:19], v[170:173], v[202:205], v[16:19]
	v_mfma_f32_16x16x32_bf16 v[16:19], v[182:185], v[206:209], v[16:19]
	v_mfma_f32_16x16x32_bf16 v[4:7], v[144:147], v[210:213], v[4:7]
	v_mfma_f32_16x16x32_bf16 v[4:7], v[148:151], v[214:217], v[4:7]
	v_mfma_f32_16x16x32_bf16 v[0:3], v[170:173], v[210:213], v[0:3]
	v_mfma_f32_16x16x32_bf16 v[0:3], v[182:185], v[214:217], v[0:3]
	s_setprio 0
	s_barrier
	s_add_i32 s58, 0, 0x18000
	s_add_i32 s59, 0, 0x1c000
	v_add_u32_e32 v140, s58, v174
	v_add_u32_e32 v181, s59, v174
	ds_read_b128 v[128:131], v140
	ds_read_b128 v[132:135], v140 offset:1024
	ds_read_b128 v[136:139], v140 offset:2048
	ds_read_b128 v[140:143], v140 offset:3072
	ds_read_b128 v[144:147], v181
	ds_read_b128 v[148:151], v181 offset:1024
	ds_read_b128 v[170:173], v181 offset:2048
	ds_read_b128 v[182:185], v181 offset:3072
	s_add_u32 s26, s26, 0x400000
	s_addc_u32 s27, s27, 0
	s_mov_b32 m0, s40
	v_lshl_add_u64 v[186:187], s[26:27], 0, v[152:153]
	global_load_lds_dwordx4 v[186:187], off
	v_lshl_add_u64 v[186:187], s[26:27], 0, v[156:157]
	s_mov_b32 m0, s41
	s_nop 0
	global_load_lds_dwordx4 v[186:187], off
	ds_read_b128 v[186:189], v179 offset:32768
	ds_read_b128 v[190:193], v179 offset:33792
	ds_read_b128 v[194:197], v179 offset:34816
	ds_read_b128 v[198:201], v179 offset:35840
	ds_read_b128 v[202:205], v179 offset:36864
	ds_read_b128 v[206:209], v179 offset:37888
	ds_read_b128 v[210:213], v179 offset:38912
	ds_read_b128 v[214:217], v179 offset:39936
	s_waitcnt vmcnt(8)
	s_waitcnt lgkmcnt(0)
	s_barrier
	s_setprio 1
	s_waitcnt lgkmcnt(0)
	v_mfma_f32_16x16x32_bf16 v[124:127], v[128:131], v[186:189], v[124:127]
	v_mfma_f32_16x16x32_bf16 v[124:127], v[132:135], v[190:193], v[124:127]
	v_mfma_f32_16x16x32_bf16 v[120:123], v[136:139], v[186:189], v[120:123]
	v_mfma_f32_16x16x32_bf16 v[120:123], v[140:143], v[190:193], v[120:123]
	v_mfma_f32_16x16x32_bf16 v[108:111], v[128:131], v[194:197], v[108:111]
	v_mfma_f32_16x16x32_bf16 v[108:111], v[132:135], v[198:201], v[108:111]
	v_mfma_f32_16x16x32_bf16 v[104:107], v[136:139], v[194:197], v[104:107]
	v_mfma_f32_16x16x32_bf16 v[104:107], v[140:143], v[198:201], v[104:107]
	v_mfma_f32_16x16x32_bf16 v[92:95], v[128:131], v[202:205], v[92:95]
	v_mfma_f32_16x16x32_bf16 v[92:95], v[132:135], v[206:209], v[92:95]
	v_mfma_f32_16x16x32_bf16 v[88:91], v[136:139], v[202:205], v[88:91]
	v_mfma_f32_16x16x32_bf16 v[88:91], v[140:143], v[206:209], v[88:91]
	v_mfma_f32_16x16x32_bf16 v[76:79], v[128:131], v[210:213], v[76:79]
	v_mfma_f32_16x16x32_bf16 v[76:79], v[132:135], v[214:217], v[76:79]
	v_mfma_f32_16x16x32_bf16 v[72:75], v[136:139], v[210:213], v[72:75]
	v_mfma_f32_16x16x32_bf16 v[72:75], v[140:143], v[214:217], v[72:75]
	s_setprio 0
	s_setprio 1
	v_mfma_f32_16x16x32_bf16 v[116:119], v[144:147], v[186:189], v[116:119]
	v_mfma_f32_16x16x32_bf16 v[116:119], v[148:151], v[190:193], v[116:119]
	v_mfma_f32_16x16x32_bf16 v[112:115], v[170:173], v[186:189], v[112:115]
	v_mfma_f32_16x16x32_bf16 v[112:115], v[182:185], v[190:193], v[112:115]
	v_mfma_f32_16x16x32_bf16 v[100:103], v[144:147], v[194:197], v[100:103]
	v_mfma_f32_16x16x32_bf16 v[100:103], v[148:151], v[198:201], v[100:103]
	v_mfma_f32_16x16x32_bf16 v[96:99], v[170:173], v[194:197], v[96:99]
	v_mfma_f32_16x16x32_bf16 v[96:99], v[182:185], v[198:201], v[96:99]
	v_mfma_f32_16x16x32_bf16 v[84:87], v[144:147], v[202:205], v[84:87]
	v_mfma_f32_16x16x32_bf16 v[84:87], v[148:151], v[206:209], v[84:87]
	v_mfma_f32_16x16x32_bf16 v[80:83], v[170:173], v[202:205], v[80:83]
	v_mfma_f32_16x16x32_bf16 v[80:83], v[182:185], v[206:209], v[80:83]
	v_mfma_f32_16x16x32_bf16 v[68:71], v[144:147], v[210:213], v[68:71]
	v_mfma_f32_16x16x32_bf16 v[68:71], v[148:151], v[214:217], v[68:71]
	v_mfma_f32_16x16x32_bf16 v[64:67], v[170:173], v[210:213], v[64:67]
	v_mfma_f32_16x16x32_bf16 v[64:67], v[182:185], v[214:217], v[64:67]
	s_setprio 0
	s_barrier
	s_add_i32 s26, s58, s37
	v_lshl_add_u64 v[186:187], v[218:219], 0, s[14:15]
	s_mov_b32 m0, s26
	s_nop 0
	global_load_lds_dwordx4 v[186:187], off
	s_add_i32 m0, s26, 0x2000
	s_add_u32 s24, s24, 0x400800
	v_lshl_add_u64 v[186:187], v[220:221], 0, s[14:15]
	s_addc_u32 s25, s25, 0
	s_add_i32 s26, s59, s37
	global_load_lds_dwordx4 v[186:187], off
	v_lshl_add_u64 v[186:187], s[24:25], 0, v[154:155]
	s_mov_b32 m0, s26
	s_nop 0
	global_load_lds_dwordx4 v[186:187], off
	v_lshl_add_u64 v[186:187], s[24:25], 0, v[158:159]
	s_add_i32 m0, s26, 0x2000
	s_nop 0
	global_load_lds_dwordx4 v[186:187], off
	v_lshl_add_u64 v[186:187], v[222:223], 0, s[14:15]
	s_mov_b32 m0, s43
	s_nop 0
	global_load_lds_dwordx4 v[186:187], off
	v_lshl_add_u64 v[186:187], v[224:225], 0, s[14:15]
	s_mov_b32 m0, s44
	s_nop 0
	global_load_lds_dwordx4 v[186:187], off
	ds_read_b128 v[186:189], v179 offset:49152
	ds_read_b128 v[190:193], v179 offset:50176
	ds_read_b128 v[194:197], v179 offset:51200
	ds_read_b128 v[198:201], v179 offset:52224
	ds_read_b128 v[202:205], v179 offset:53248
	ds_read_b128 v[206:209], v179 offset:54272
	ds_read_b128 v[210:213], v179 offset:55296
	ds_read_b128 v[214:217], v179 offset:56320
	s_waitcnt vmcnt(8)
	s_waitcnt lgkmcnt(0)
	s_barrier
	s_setprio 1
	s_waitcnt lgkmcnt(0)
	v_mfma_f32_16x16x32_bf16 v[60:63], v[128:131], v[186:189], v[60:63]
	v_mfma_f32_16x16x32_bf16 v[60:63], v[132:135], v[190:193], v[60:63]
	v_mfma_f32_16x16x32_bf16 v[56:59], v[136:139], v[186:189], v[56:59]
	v_mfma_f32_16x16x32_bf16 v[56:59], v[140:143], v[190:193], v[56:59]
	v_mfma_f32_16x16x32_bf16 v[44:47], v[128:131], v[194:197], v[44:47]
	v_mfma_f32_16x16x32_bf16 v[44:47], v[132:135], v[198:201], v[44:47]
	v_mfma_f32_16x16x32_bf16 v[40:43], v[136:139], v[194:197], v[40:43]
	v_mfma_f32_16x16x32_bf16 v[40:43], v[140:143], v[198:201], v[40:43]
	v_mfma_f32_16x16x32_bf16 v[28:31], v[128:131], v[202:205], v[28:31]
	v_mfma_f32_16x16x32_bf16 v[28:31], v[132:135], v[206:209], v[28:31]
	v_mfma_f32_16x16x32_bf16 v[24:27], v[136:139], v[202:205], v[24:27]
	v_mfma_f32_16x16x32_bf16 v[24:27], v[140:143], v[206:209], v[24:27]
	v_mfma_f32_16x16x32_bf16 v[12:15], v[128:131], v[210:213], v[12:15]
	v_mfma_f32_16x16x32_bf16 v[12:15], v[132:135], v[214:217], v[12:15]
	v_mfma_f32_16x16x32_bf16 v[8:11], v[136:139], v[210:213], v[8:11]
	v_mfma_f32_16x16x32_bf16 v[8:11], v[140:143], v[214:217], v[8:11]
	s_setprio 0
	s_setprio 1
	v_mfma_f32_16x16x32_bf16 v[52:55], v[144:147], v[186:189], v[52:55]
	v_mfma_f32_16x16x32_bf16 v[52:55], v[148:151], v[190:193], v[52:55]
	v_mfma_f32_16x16x32_bf16 v[48:51], v[170:173], v[186:189], v[48:51]
	v_mfma_f32_16x16x32_bf16 v[48:51], v[182:185], v[190:193], v[48:51]
	v_mfma_f32_16x16x32_bf16 v[36:39], v[144:147], v[194:197], v[36:39]
	v_mfma_f32_16x16x32_bf16 v[36:39], v[148:151], v[198:201], v[36:39]
	v_mfma_f32_16x16x32_bf16 v[32:35], v[170:173], v[194:197], v[32:35]
	v_mfma_f32_16x16x32_bf16 v[32:35], v[182:185], v[198:201], v[32:35]
	v_mfma_f32_16x16x32_bf16 v[20:23], v[144:147], v[202:205], v[20:23]
	v_mfma_f32_16x16x32_bf16 v[20:23], v[148:151], v[206:209], v[20:23]
	v_mfma_f32_16x16x32_bf16 v[16:19], v[170:173], v[202:205], v[16:19]
	v_mfma_f32_16x16x32_bf16 v[16:19], v[182:185], v[206:209], v[16:19]
	v_mfma_f32_16x16x32_bf16 v[4:7], v[144:147], v[210:213], v[4:7]
	v_mfma_f32_16x16x32_bf16 v[4:7], v[148:151], v[214:217], v[4:7]
	v_mfma_f32_16x16x32_bf16 v[0:3], v[170:173], v[210:213], v[0:3]
	v_mfma_f32_16x16x32_bf16 v[0:3], v[182:185], v[214:217], v[0:3]
	s_setprio 0
	s_barrier
	s_add_i32 s57, s57, 2
	s_add_u32 s22, s22, 0x1000
	s_addc_u32 s23, s23, 0
	s_add_u32 s55, s55, 0x1000
	s_addc_u32 s56, s56, 0
	s_cmpk_gt_u32 s57, 0xfd
	s_cbranch_scc0 .LBB0_1625
	s_and_b64 vcc, exec, s[6:7]
	s_cbranch_vccz .LBB0_1628
	s_barrier
